# v46 + gsu epilogue loads issued together (counted waits) + conv output stage: identical parameter reloads in iterations 2-4 removed
# speedup vs baseline: 1.0123x; 1.0002x over previous
.LBB0_836:
	s_or_b32 s24, s44, s91
	v_mad_u64_u32 v[0:1], s[6:7], s24, v211, v[16:17]
	s_or_b32 s6, s24, 1
	s_nop 0
	v_mad_u64_u32 v[2:3], s[6:7], s6, v211, v[16:17]
	s_or_b32 s6, s24, 2
	s_nop 0
	v_mad_u64_u32 v[4:5], s[6:7], s6, v211, v[16:17]
	s_or_b32 s6, s24, 3
	s_nop 0
	v_mad_u64_u32 v[6:7], s[6:7], s6, v211, v[16:17]
	s_or_b32 s6, s24, 4
	s_nop 0
	v_mad_u64_u32 v[8:9], s[6:7], s6, v211, v[16:17]
	s_or_b32 s6, s24, 5
	s_nop 0
	v_mad_u64_u32 v[10:11], s[6:7], s6, v211, v[16:17]
	s_or_b32 s6, s24, 6
	s_nop 0
	v_mad_u64_u32 v[22:23], s[6:7], s6, v211, v[16:17]
	s_or_b32 s6, s24, 7
	s_nop 0
	v_mad_u64_u32 v[24:25], s[6:7], s6, v211, v[16:17]
	s_or_b32 s6, s24, 8
	s_nop 0
	v_mad_u64_u32 v[26:27], s[6:7], s6, v211, v[16:17]
	s_or_b32 s6, s24, 9
	s_nop 0
	v_mad_u64_u32 v[28:29], s[6:7], s6, v211, v[16:17]
	s_or_b32 s6, s24, 10
	s_nop 0
	v_mad_u64_u32 v[30:31], s[6:7], s6, v211, v[16:17]
	s_or_b32 s6, s24, 11
	s_nop 0
	v_mad_u64_u32 v[32:33], s[6:7], s6, v211, v[16:17]
	s_or_b32 s6, s24, 12
	s_nop 0
	v_mad_u64_u32 v[34:35], s[6:7], s6, v211, v[16:17]
	s_or_b32 s6, s24, 13
	s_nop 0
	v_mad_u64_u32 v[36:37], s[6:7], s6, v211, v[16:17]
	s_or_b32 s6, s24, 14
	s_nop 0
	v_mad_u64_u32 v[38:39], s[6:7], s6, v211, v[16:17]
	s_or_b32 s6, s24, 15
	s_nop 0
	v_mad_u64_u32 v[40:41], s[6:7], s6, v211, v[16:17]
	s_or_b32 s6, s24, 16
	s_nop 0
	v_mad_u64_u32 v[42:43], s[6:7], s6, v211, v[16:17]
	s_or_b32 s6, s24, 17
	s_nop 0
	v_mad_u64_u32 v[44:45], s[6:7], s6, v211, v[16:17]
	s_or_b32 s6, s24, 18
	s_nop 0
	v_mad_u64_u32 v[46:47], s[6:7], s6, v211, v[16:17]
	s_or_b32 s6, s24, 19
	s_nop 0
	v_mad_u64_u32 v[50:51], s[6:7], s6, v211, v[16:17]
	s_or_b32 s6, s24, 20
	s_nop 0
	v_mad_u64_u32 v[52:53], s[6:7], s6, v211, v[16:17]
	s_or_b32 s6, s24, 21
	s_nop 0
	v_mad_u64_u32 v[54:55], s[6:7], s6, v211, v[16:17]
	s_or_b32 s6, s24, 22
	s_nop 0
	v_mad_u64_u32 v[56:57], s[6:7], s6, v211, v[16:17]
	s_or_b32 s6, s24, 23
	s_nop 0
	v_mad_u64_u32 v[58:59], s[6:7], s6, v211, v[16:17]
	s_or_b32 s6, s24, 24
	s_nop 0
	v_mad_u64_u32 v[60:61], s[6:7], s6, v211, v[16:17]
	s_or_b32 s6, s24, 25
	s_nop 0
	v_mad_u64_u32 v[62:63], s[6:7], s6, v211, v[16:17]
	s_or_b32 s6, s24, 26
	s_nop 0
	v_mad_u64_u32 v[64:65], s[6:7], s6, v211, v[16:17]
	s_or_b32 s6, s24, 27
	s_nop 0
	v_mad_u64_u32 v[66:67], s[6:7], s6, v211, v[16:17]
	s_or_b32 s6, s24, 28
	s_nop 0
	v_mad_u64_u32 v[68:69], s[6:7], s6, v211, v[16:17]
	s_or_b32 s6, s24, 29
	s_nop 0
	v_mad_u64_u32 v[70:71], s[6:7], s6, v211, v[16:17]
	s_or_b32 s6, s24, 30
	s_nop 0
	v_mad_u64_u32 v[72:73], s[6:7], s6, v211, v[16:17]
	s_or_b32 s6, s24, 31
	s_mul_i32 s8, s45, 0xc00
	v_mad_u64_u32 v[106:107], s[6:7], s6, v211, v[16:17]
	v_add_u32_e32 v107, s8, v107
	global_load_ushort v108, v[106:107], off offset:1856
	v_add_u32_e32 v1, s8, v1
	v_add_u32_e32 v3, s8, v3
	v_add_u32_e32 v5, s8, v5
	v_add_u32_e32 v7, s8, v7
	v_add_u32_e32 v9, s8, v9
	v_add_u32_e32 v11, s8, v11
	v_add_u32_e32 v23, s8, v23
	v_add_u32_e32 v25, s8, v25
	v_add_u32_e32 v27, s8, v27
	v_add_u32_e32 v29, s8, v29
	v_add_u32_e32 v31, s8, v31
	v_add_u32_e32 v33, s8, v33
	v_add_u32_e32 v35, s8, v35
	v_add_u32_e32 v37, s8, v37
	v_add_u32_e32 v39, s8, v39
	v_add_u32_e32 v41, s8, v41
	v_add_u32_e32 v43, s8, v43
	v_add_u32_e32 v45, s8, v45
	v_add_u32_e32 v47, s8, v47
	v_add_u32_e32 v51, s8, v51
	v_add_u32_e32 v53, s8, v53
	v_add_u32_e32 v55, s8, v55
	v_add_u32_e32 v57, s8, v57
	v_add_u32_e32 v59, s8, v59
	v_add_u32_e32 v61, s8, v61
	v_add_u32_e32 v63, s8, v63
	v_add_u32_e32 v65, s8, v65
	v_add_u32_e32 v67, s8, v67
	v_add_u32_e32 v69, s8, v69
	v_add_u32_e32 v71, s8, v71
	v_add_u32_e32 v73, s8, v73
	global_load_ushort v106, v[106:107], off offset:832
	v_readlane_b32 s6, v255, 37
	global_load_ushort v107, v[72:73], off offset:1856
	s_mul_i32 s6, s6, 0xf800
	global_load_ushort v72, v[72:73], off offset:832
	s_add_u32 s6, s54, s6
	global_load_ushort v73, v[70:71], off offset:1856
	s_addc_u32 s7, s55, 0
	global_load_ushort v70, v[70:71], off offset:832
	s_add_u32 s40, s56, s42
	global_load_ushort v71, v[68:69], off offset:1856
	s_addc_u32 s41, s57, s43
	global_load_ushort v68, v[68:69], off offset:832
	s_movk_i32 s8, 0xc00
	global_load_ushort v69, v[66:67], off offset:1856
	s_waitcnt vmcnt(8)
	v_lshlrev_b32_e32 v108, 16, v108
	global_load_ushort v66, v[66:67], off offset:832
	v_mul_f32_e32 v108, 0xbfb8aa3b, v108
	global_load_ushort v67, v[64:65], off offset:1856
	v_exp_f32_e32 v108, v108
	global_load_ushort v64, v[64:65], off offset:832
	v_add_f32_e32 v108, 1.0, v108
	global_load_ushort v65, v[62:63], off offset:1856
	v_rcp_f32_e32 v108, v108
	global_load_ushort v62, v[62:63], off offset:832
	s_waitcnt vmcnt(12)
	v_lshlrev_b32_e32 v106, 16, v106
	global_load_ushort v63, v[60:61], off offset:1856
	v_mul_f32_e32 v106, v108, v106
	global_load_ushort v60, v[60:61], off offset:832
	v_lshl_add_u64 v[108:109], s[6:7], 0, v[20:21]
	global_load_ushort v61, v[58:59], off offset:1856
	s_movk_i32 s6, 0x1000
	global_load_ushort v58, v[58:59], off offset:832
	v_add_co_u32_e32 v110, vcc, s6, v108
	global_load_ushort v59, v[56:57], off offset:1856
	s_nop 0
	v_addc_co_u32_e32 v111, vcc, 0, v109, vcc
	global_load_ushort v56, v[56:57], off offset:832
	s_movk_i32 s6, 0x2000
	global_load_ushort v57, v[54:55], off offset:1856
	v_add_co_u32_e32 v112, vcc, s6, v108
	global_load_ushort v54, v[54:55], off offset:832
	s_nop 0
	v_addc_co_u32_e32 v113, vcc, 0, v109, vcc
	global_load_ushort v55, v[52:53], off offset:1856
	s_movk_i32 s6, 0x3000
	global_load_ushort v52, v[52:53], off offset:832
	s_waitcnt vmcnt(19)
	v_lshlrev_b32_e32 v73, 16, v73
	global_load_ushort v53, v[50:51], off offset:1856
	s_waitcnt vmcnt(18)
	v_lshlrev_b32_e32 v71, 16, v71
	global_load_ushort v50, v[50:51], off offset:832
	s_waitcnt vmcnt(17)
	v_lshlrev_b32_e32 v69, 16, v69
	global_load_ushort v51, v[46:47], off offset:1856
	v_lshlrev_b32_e32 v107, 16, v107
	global_load_ushort v46, v[46:47], off offset:832
	v_mul_f32_e32 v73, 0xbfb8aa3b, v73
	global_load_ushort v47, v[44:45], off offset:1856
	v_mul_f32_e32 v71, 0xbfb8aa3b, v71
	global_load_ushort v44, v[44:45], off offset:832
	v_mul_f32_e32 v69, 0xbfb8aa3b, v69
	global_load_ushort v45, v[42:43], off offset:1856
	v_mul_f32_e32 v107, 0xbfb8aa3b, v107
	global_load_ushort v42, v[42:43], off offset:832
	v_exp_f32_e32 v73, v73
	global_load_ushort v43, v[40:41], off offset:1856
	v_exp_f32_e32 v71, v71
	global_load_ushort v40, v[40:41], off offset:832
	v_exp_f32_e32 v69, v69
	global_load_ushort v41, v[38:39], off offset:1856
	v_exp_f32_e32 v107, v107
	global_load_ushort v38, v[38:39], off offset:832
	v_add_f32_e32 v73, 1.0, v73
	global_load_ushort v39, v[36:37], off offset:1856
	v_add_f32_e32 v71, 1.0, v71
	global_load_ushort v36, v[36:37], off offset:832
	s_waitcnt vmcnt(27)
	v_lshlrev_b32_e32 v67, 16, v67
	global_load_ushort v37, v[34:35], off offset:1856
	v_mul_f32_e32 v67, 0xbfb8aa3b, v67
	global_load_ushort v34, v[34:35], off offset:832
	v_exp_f32_e32 v67, v67
	global_load_ushort v35, v[32:33], off offset:1856
	s_waitcnt vmcnt(28)
	v_lshlrev_b32_e32 v65, 16, v65
	global_load_ushort v32, v[32:33], off offset:832
	v_mul_f32_e32 v65, 0xbfb8aa3b, v65
	global_load_ushort v33, v[30:31], off offset:1856
	v_exp_f32_e32 v65, v65
	global_load_ushort v30, v[30:31], off offset:832
	v_add_f32_e32 v69, 1.0, v69
	global_load_ushort v31, v[28:29], off offset:1856
	v_add_f32_e32 v67, 1.0, v67
	global_load_ushort v28, v[28:29], off offset:832
	v_add_f32_e32 v65, 1.0, v65
	global_load_ushort v29, v[26:27], off offset:1856
	v_add_f32_e32 v107, 1.0, v107
	global_load_ushort v26, v[26:27], off offset:832
	v_rcp_f32_e32 v73, v73
	global_load_ushort v27, v[24:25], off offset:1856
	v_rcp_f32_e32 v71, v71
	global_load_ushort v24, v[24:25], off offset:832
	v_rcp_f32_e32 v69, v69
	global_load_ushort v25, v[22:23], off offset:1856
	v_rcp_f32_e32 v67, v67
	global_load_ushort v22, v[22:23], off offset:832
	v_rcp_f32_e32 v65, v65
	global_load_ushort v23, v[10:11], off offset:1856
	s_waitcnt vmcnt(38)
	v_lshlrev_b32_e32 v63, 16, v63
	global_load_ushort v10, v[10:11], off offset:832
	v_mul_f32_e32 v63, 0xbfb8aa3b, v63
	global_load_ushort v11, v[8:9], off offset:1856
	s_waitcnt vmcnt(38)
	v_lshlrev_b32_e32 v61, 16, v61
	global_load_ushort v8, v[8:9], off offset:832
	v_mul_f32_e32 v61, 0xbfb8aa3b, v61
	global_load_ushort v9, v[6:7], off offset:1856
	s_waitcnt vmcnt(38)
	v_lshlrev_b32_e32 v59, 16, v59
	global_load_ushort v6, v[6:7], off offset:832
	v_mul_f32_e32 v59, 0xbfb8aa3b, v59
	global_load_ushort v7, v[4:5], off offset:1856
	v_exp_f32_e32 v63, v63
	global_load_ushort v4, v[4:5], off offset:832
	s_waitcnt vmcnt(39)
	v_lshlrev_b32_e32 v57, 16, v57
	global_load_ushort v5, v[2:3], off offset:1856
	v_mul_f32_e32 v57, 0xbfb8aa3b, v57
	global_load_ushort v2, v[2:3], off offset:832
	v_exp_f32_e32 v61, v61
	global_load_ushort v3, v[0:1], off offset:1856
	s_waitcnt vmcnt(40)
	v_lshlrev_b32_e32 v55, 16, v55
	global_load_ushort v0, v[0:1], off offset:832
	v_mul_f32_e32 v55, 0xbfb8aa3b, v55
	s_waitcnt vmcnt(39)
	v_lshlrev_b32_e32 v53, 16, v53
	v_mul_f32_e32 v53, 0xbfb8aa3b, v53
	v_exp_f32_e32 v55, v55
	v_exp_f32_e32 v53, v53
	s_waitcnt vmcnt(37)
	v_lshlrev_b32_e32 v51, 16, v51
	v_mul_f32_e32 v51, 0xbfb8aa3b, v51
	v_exp_f32_e32 v51, v51
	v_exp_f32_e32 v59, v59
	s_waitcnt vmcnt(35)
	v_lshlrev_b32_e32 v47, 16, v47
	v_mul_f32_e32 v47, 0xbfb8aa3b, v47
	v_exp_f32_e32 v47, v47
	v_exp_f32_e32 v57, v57
	s_waitcnt vmcnt(33)
	v_lshlrev_b32_e32 v45, 16, v45
	v_mul_f32_e32 v45, 0xbfb8aa3b, v45
	v_exp_f32_e32 v45, v45
	v_add_f32_e32 v55, 1.0, v55
	s_waitcnt vmcnt(31)
	v_lshlrev_b32_e32 v43, 16, v43
	v_mul_f32_e32 v43, 0xbfb8aa3b, v43
	v_exp_f32_e32 v43, v43
	v_add_f32_e32 v45, 1.0, v45
	s_waitcnt vmcnt(29)
	v_lshlrev_b32_e32 v41, 16, v41
	v_mul_f32_e32 v41, 0xbfb8aa3b, v41
	v_exp_f32_e32 v41, v41
	v_add_f32_e32 v43, 1.0, v43
	s_waitcnt vmcnt(27)
	v_lshlrev_b32_e32 v39, 16, v39
	v_mul_f32_e32 v39, 0xbfb8aa3b, v39
	v_exp_f32_e32 v39, v39
	v_add_f32_e32 v41, 1.0, v41
	s_waitcnt vmcnt(25)
	v_lshlrev_b32_e32 v37, 16, v37
	v_mul_f32_e32 v37, 0xbfb8aa3b, v37
	v_exp_f32_e32 v37, v37
	s_waitcnt vmcnt(24)
	v_lshlrev_b32_e32 v34, 16, v34
	s_waitcnt vmcnt(23)
	v_lshlrev_b32_e32 v35, 16, v35
	v_mul_f32_e32 v35, 0xbfb8aa3b, v35
	v_add_f32_e32 v37, 1.0, v37
	v_rcp_f32_e32 v37, v37
	s_waitcnt vmcnt(21)
	v_lshlrev_b32_e32 v33, 16, v33
	v_mul_f32_e32 v33, 0xbfb8aa3b, v33
	v_exp_f32_e32 v35, v35
	v_exp_f32_e32 v33, v33
	s_waitcnt vmcnt(19)
	v_lshlrev_b32_e32 v31, 16, v31
	v_mul_f32_e32 v31, 0xbfb8aa3b, v31
	v_exp_f32_e32 v31, v31
	v_mul_f32_e32 v34, v37, v34
	s_waitcnt vmcnt(17)
	v_lshlrev_b32_e32 v29, 16, v29
	v_mul_f32_e32 v29, 0xbfb8aa3b, v29
	v_exp_f32_e32 v29, v29
	v_add_f32_e32 v35, 1.0, v35
	s_waitcnt vmcnt(15)
	v_lshlrev_b32_e32 v27, 16, v27
	v_mul_f32_e32 v27, 0xbfb8aa3b, v27
	v_exp_f32_e32 v27, v27
	v_add_f32_e32 v33, 1.0, v33
	s_waitcnt vmcnt(13)
	v_lshlrev_b32_e32 v25, 16, v25
	v_mul_f32_e32 v25, 0xbfb8aa3b, v25
	v_exp_f32_e32 v25, v25
	v_add_f32_e32 v27, 1.0, v27
	s_waitcnt vmcnt(11)
	v_lshlrev_b32_e32 v23, 16, v23
	v_mul_f32_e32 v23, 0xbfb8aa3b, v23
	v_exp_f32_e32 v23, v23
	v_add_f32_e32 v25, 1.0, v25
	s_waitcnt vmcnt(9)
	v_lshlrev_b32_e32 v11, 16, v11
	v_mul_f32_e32 v11, 0xbfb8aa3b, v11
	v_exp_f32_e32 v11, v11
	v_add_f32_e32 v23, 1.0, v23
	s_waitcnt vmcnt(7)
	v_lshlrev_b32_e32 v9, 16, v9
	v_mul_f32_e32 v9, 0xbfb8aa3b, v9
	v_exp_f32_e32 v9, v9
	v_add_f32_e32 v11, 1.0, v11
	s_waitcnt vmcnt(5)
	v_lshlrev_b32_e32 v7, 16, v7
	v_mul_f32_e32 v7, 0xbfb8aa3b, v7
	v_exp_f32_e32 v7, v7
	v_add_f32_e32 v9, 1.0, v9
	s_waitcnt vmcnt(3)
	v_lshlrev_b32_e32 v5, 16, v5
	v_mul_f32_e32 v5, 0xbfb8aa3b, v5
	v_exp_f32_e32 v5, v5
	v_add_f32_e32 v7, 1.0, v7
	s_waitcnt vmcnt(1)
	v_lshlrev_b32_e32 v3, 16, v3
	v_mul_f32_e32 v3, 0xbfb8aa3b, v3
	v_exp_f32_e32 v3, v3
	v_add_f32_e32 v5, 1.0, v5
	v_rcp_f32_e32 v9, v9
	v_rcp_f32_e32 v7, v7
	v_add_f32_e32 v3, 1.0, v3
	v_rcp_f32_e32 v5, v5
	v_rcp_f32_e32 v3, v3
	v_lshlrev_b32_e32 v6, 16, v6
	v_lshlrev_b32_e32 v4, 16, v4
	v_lshlrev_b32_e32 v2, 16, v2
	s_waitcnt vmcnt(0)
	v_lshlrev_b32_e32 v0, 16, v0
	v_rcp_f32_e32 v27, v27
	v_rcp_f32_e32 v25, v25
	v_rcp_f32_e32 v23, v23
	v_rcp_f32_e32 v11, v11
	v_mul_f32_e32 v6, v9, v6
	v_mul_f32_e32 v4, v7, v4
	v_mul_f32_e32 v2, v5, v2
	v_mul_f32_e32 v37, v3, v0
	global_load_dword v0, v[108:109], off
	global_load_dword v1, v[108:109], off offset:2048
	global_load_dword v3, v[112:113], off offset:-4096
	global_load_dword v5, v[110:111], off offset:2048
	global_load_dword v7, v[112:113], off
	global_load_dword v9, v[112:113], off offset:2048
	v_add_co_u32_e32 v110, vcc, s6, v108
	s_movk_i32 s6, 0x4000
	s_nop 0
	v_addc_co_u32_e32 v111, vcc, 0, v109, vcc
	v_add_co_u32_e32 v112, vcc, s6, v108
	v_add_f32_e32 v31, 1.0, v31
	v_add_f32_e32 v29, 1.0, v29
	v_lshlrev_b32_e32 v24, 16, v24
	v_lshlrev_b32_e32 v22, 16, v22
	v_lshlrev_b32_e32 v10, 16, v10
	v_lshlrev_b32_e32 v8, 16, v8
	v_addc_co_u32_e32 v113, vcc, 0, v109, vcc
	s_movk_i32 s6, 0x5000
	v_rcp_f32_e32 v35, v35
	v_rcp_f32_e32 v33, v33
	v_rcp_f32_e32 v31, v31
	v_rcp_f32_e32 v29, v29
	v_mul_f32_e32 v24, v27, v24
	v_mul_f32_e32 v22, v25, v22
	v_mul_f32_e32 v10, v23, v10
	v_mul_f32_e32 v8, v11, v8
	global_load_dword v11, v[112:113], off offset:-4096
	global_load_dword v23, v[110:111], off offset:2048
	global_load_dword v25, v[112:113], off
	global_load_dword v27, v[112:113], off offset:2048
	v_add_co_u32_e32 v110, vcc, s6, v108
	s_movk_i32 s6, 0x6000
	s_nop 0
	v_addc_co_u32_e32 v111, vcc, 0, v109, vcc
	v_add_co_u32_e32 v112, vcc, s6, v108
	v_add_f32_e32 v39, 1.0, v39
	v_lshlrev_b32_e32 v32, 16, v32
	v_lshlrev_b32_e32 v30, 16, v30
	v_lshlrev_b32_e32 v28, 16, v28
	v_lshlrev_b32_e32 v26, 16, v26
	v_addc_co_u32_e32 v113, vcc, 0, v109, vcc
	s_movk_i32 s6, 0x7000
	v_rcp_f32_e32 v45, v45
	v_rcp_f32_e32 v43, v43
	v_rcp_f32_e32 v41, v41
	v_rcp_f32_e32 v39, v39
	v_mul_f32_e32 v32, v35, v32
	v_mul_f32_e32 v30, v33, v30
	v_mul_f32_e32 v28, v31, v28
	v_mul_f32_e32 v26, v29, v26
	global_load_dword v29, v[112:113], off offset:-4096
	global_load_dword v31, v[110:111], off offset:2048
	global_load_dword v33, v[112:113], off
	global_load_dword v35, v[112:113], off offset:2048
	v_add_co_u32_e32 v110, vcc, s6, v108
	s_mov_b32 s6, 0x8000
	s_nop 0
	v_addc_co_u32_e32 v111, vcc, 0, v109, vcc
	v_add_co_u32_e32 v112, vcc, s6, v108
	v_add_f32_e32 v53, 1.0, v53
	v_add_f32_e32 v51, 1.0, v51
	v_add_f32_e32 v47, 1.0, v47
	v_lshlrev_b32_e32 v42, 16, v42
	v_lshlrev_b32_e32 v40, 16, v40
	v_lshlrev_b32_e32 v38, 16, v38
	v_lshlrev_b32_e32 v36, 16, v36
	v_addc_co_u32_e32 v113, vcc, 0, v109, vcc
	s_mov_b32 s6, 0x9000
	v_rcp_f32_e32 v55, v55
	v_rcp_f32_e32 v53, v53
	v_rcp_f32_e32 v51, v51
	v_rcp_f32_e32 v47, v47
	v_mul_f32_e32 v42, v45, v42
	v_mul_f32_e32 v40, v43, v40
	v_mul_f32_e32 v38, v41, v38
	v_mul_f32_e32 v36, v39, v36
	global_load_dword v39, v[112:113], off offset:-4096
	global_load_dword v41, v[110:111], off offset:2048
	global_load_dword v43, v[112:113], off
	global_load_dword v45, v[112:113], off offset:2048
	v_add_co_u32_e32 v110, vcc, s6, v108
	s_mov_b32 s6, 0xa000
	s_nop 0
	v_addc_co_u32_e32 v111, vcc, 0, v109, vcc
	v_add_co_u32_e32 v112, vcc, s6, v108
	v_add_f32_e32 v63, 1.0, v63
	v_add_f32_e32 v61, 1.0, v61
	v_add_f32_e32 v59, 1.0, v59
	v_add_f32_e32 v57, 1.0, v57
	v_lshlrev_b32_e32 v52, 16, v52
	v_lshlrev_b32_e32 v50, 16, v50
	v_lshlrev_b32_e32 v46, 16, v46
	v_lshlrev_b32_e32 v44, 16, v44
	v_addc_co_u32_e32 v113, vcc, 0, v109, vcc
	s_mov_b32 s6, 0xb000
	v_rcp_f32_e32 v63, v63
	v_rcp_f32_e32 v61, v61
	v_rcp_f32_e32 v59, v59
	v_rcp_f32_e32 v57, v57
	v_mul_f32_e32 v52, v55, v52
	v_mul_f32_e32 v50, v53, v50
	v_mul_f32_e32 v46, v51, v46
	v_mul_f32_e32 v44, v47, v44
	global_load_dword v47, v[112:113], off offset:-4096
	global_load_dword v51, v[110:111], off offset:2048
	global_load_dword v53, v[112:113], off
	global_load_dword v55, v[112:113], off offset:2048
	v_add_co_u32_e32 v110, vcc, s6, v108
	s_mov_b32 s6, 0xc000
	s_nop 0
	v_addc_co_u32_e32 v111, vcc, 0, v109, vcc
	v_add_co_u32_e32 v112, vcc, s6, v108
	v_lshlrev_b32_e32 v60, 16, v60
	v_lshlrev_b32_e32 v58, 16, v58
	v_lshlrev_b32_e32 v56, 16, v56
	v_lshlrev_b32_e32 v54, 16, v54
	v_addc_co_u32_e32 v113, vcc, 0, v109, vcc
	s_mov_b32 s6, 0xd000
	v_mul_f32_e32 v60, v63, v60
	v_mul_f32_e32 v58, v61, v58
	v_mul_f32_e32 v56, v59, v56
	v_mul_f32_e32 v54, v57, v54
	global_load_dword v57, v[112:113], off offset:-4096
	global_load_dword v59, v[110:111], off offset:2048
	global_load_dword v61, v[112:113], off
	global_load_dword v63, v[112:113], off offset:2048
	v_add_co_u32_e32 v110, vcc, s6, v108
	s_mov_b32 s6, 0xe000
	s_nop 0
	v_addc_co_u32_e32 v111, vcc, 0, v109, vcc
	v_add_co_u32_e32 v112, vcc, s6, v108
	v_rcp_f32_e32 v107, v107
	s_nop 0
	v_addc_co_u32_e32 v113, vcc, 0, v109, vcc
	s_mov_b32 s6, 0xf000
	v_add_co_u32_e32 v108, vcc, s6, v108
	s_add_u32 s6, s52, s42
	v_lshlrev_b32_e32 v70, 16, v70
	v_lshlrev_b32_e32 v68, 16, v68
	v_lshlrev_b32_e32 v66, 16, v66
	v_lshlrev_b32_e32 v64, 16, v64
	v_lshlrev_b32_e32 v62, 16, v62
	v_addc_co_u32_e32 v109, vcc, 0, v109, vcc
	s_addc_u32 s7, s53, s43
	v_lshlrev_b32_e32 v72, 16, v72
	v_mul_f32_e32 v70, v73, v70
	v_mul_f32_e32 v68, v71, v68
	v_mul_f32_e32 v66, v69, v66
	v_mul_f32_e32 v64, v67, v64
	v_mul_f32_e32 v62, v65, v62
	global_load_dword v65, v[112:113], off offset:-4096
	global_load_dword v67, v[110:111], off offset:2048
	global_load_dword v69, v[112:113], off
	global_load_dword v71, v[112:113], off offset:2048
	global_load_dword v73, v[108:109], off
	v_lshl_add_u64 v[108:109], s[6:7], 0, v[20:21]
	v_mul_f32_e32 v72, v107, v72
	global_load_dword v107, v[108:109], off
	s_add_u32 s50, s50, s42
	s_addc_u32 s51, s51, s43
	s_waitcnt vmcnt(0)
	v_fma_f32 v105, v105, v0, v107
	v_fmac_f32_e32 v105, v100, v1
	v_fma_f32 v100, v100, v0, v107
	v_fmac_f32_e32 v100, v104, v1
	v_fmac_f32_e32 v105, v104, v3
	v_fmac_f32_e32 v100, v98, v3
	v_fmac_f32_e32 v105, v98, v5
	v_fmac_f32_e32 v100, v103, v5
	v_fmac_f32_e32 v105, v103, v7
	v_fmac_f32_e32 v100, v96, v7
	v_fmac_f32_e32 v105, v96, v9
	v_fmac_f32_e32 v100, v102, v9
	v_fmac_f32_e32 v105, v102, v11
	v_fmac_f32_e32 v100, v94, v11
	v_fmac_f32_e32 v105, v94, v23
	v_fmac_f32_e32 v100, v101, v23
	v_fmac_f32_e32 v105, v101, v25
	v_fmac_f32_e32 v100, v92, v25
	v_fmac_f32_e32 v105, v92, v27
	v_fmac_f32_e32 v100, v99, v27
	v_fmac_f32_e32 v105, v99, v29
	v_fmac_f32_e32 v100, v90, v29
	v_fmac_f32_e32 v105, v90, v31
	v_fmac_f32_e32 v100, v97, v31
	v_fmac_f32_e32 v105, v97, v33
	v_fmac_f32_e32 v100, v88, v33
	v_fmac_f32_e32 v105, v88, v35
	v_fmac_f32_e32 v100, v95, v35
	v_fmac_f32_e32 v105, v95, v39
	v_fmac_f32_e32 v100, v86, v39
	v_fmac_f32_e32 v105, v86, v41
	v_fmac_f32_e32 v100, v93, v41
	v_fmac_f32_e32 v105, v93, v43
	v_fmac_f32_e32 v100, v84, v43
	v_fmac_f32_e32 v105, v84, v45
	v_fmac_f32_e32 v100, v91, v45
	v_fmac_f32_e32 v105, v91, v47
	v_fmac_f32_e32 v100, v82, v47
	v_fmac_f32_e32 v105, v82, v51
	v_fmac_f32_e32 v100, v89, v51
	v_fmac_f32_e32 v105, v89, v53
	v_fmac_f32_e32 v100, v80, v53
	v_fmac_f32_e32 v105, v80, v55
	v_fmac_f32_e32 v100, v87, v55
	v_fmac_f32_e32 v105, v87, v57
	v_fmac_f32_e32 v100, v79, v57
	v_fmac_f32_e32 v105, v79, v59
	v_fmac_f32_e32 v100, v85, v59
	v_fmac_f32_e32 v105, v85, v61
	v_fmac_f32_e32 v100, v78, v61
	v_fmac_f32_e32 v105, v78, v63
	v_fmac_f32_e32 v100, v83, v63
	v_fmac_f32_e32 v105, v83, v65
	v_fmac_f32_e32 v100, v77, v65
	v_fmac_f32_e32 v105, v77, v67
	v_fmac_f32_e32 v100, v81, v67
	v_fmac_f32_e32 v105, v81, v69
	v_fmac_f32_e32 v100, v48, v69
	v_fmac_f32_e32 v105, v48, v71
	v_fmac_f32_e32 v100, v37, v71
	v_fmac_f32_e32 v105, v37, v73
	v_fmac_f32_e32 v100, v2, v73
	ds_write2st64_b32 v15, v105, v100 offset1:8
	v_fma_f32 v100, v104, v0, v107
	v_fmac_f32_e32 v100, v98, v1
	v_fma_f32 v98, v98, v0, v107
	v_fmac_f32_e32 v98, v103, v1
	v_fmac_f32_e32 v100, v103, v3
	v_fmac_f32_e32 v98, v96, v3
	v_fmac_f32_e32 v100, v96, v5
	v_fmac_f32_e32 v98, v102, v5
	v_fmac_f32_e32 v100, v102, v7
	v_fmac_f32_e32 v98, v94, v7
	v_fmac_f32_e32 v100, v94, v9
	v_fmac_f32_e32 v98, v101, v9
	v_fmac_f32_e32 v100, v101, v11
	v_fmac_f32_e32 v98, v92, v11
	v_fmac_f32_e32 v100, v92, v23
	v_fmac_f32_e32 v98, v99, v23
	v_fmac_f32_e32 v100, v99, v25
	v_fmac_f32_e32 v98, v90, v25
	v_fmac_f32_e32 v100, v90, v27
	v_fmac_f32_e32 v98, v97, v27
	v_fmac_f32_e32 v100, v97, v29
	v_fmac_f32_e32 v98, v88, v29
	v_fmac_f32_e32 v100, v88, v31
	v_fmac_f32_e32 v98, v95, v31
	v_fmac_f32_e32 v100, v95, v33
	v_fmac_f32_e32 v98, v86, v33
	v_fmac_f32_e32 v100, v86, v35
	v_fmac_f32_e32 v98, v93, v35
	v_fmac_f32_e32 v100, v93, v39
	v_fmac_f32_e32 v98, v84, v39
	v_fmac_f32_e32 v100, v84, v41
	v_fmac_f32_e32 v98, v91, v41
	v_fmac_f32_e32 v100, v91, v43
	v_fmac_f32_e32 v98, v82, v43
	v_fmac_f32_e32 v100, v82, v45
	v_fmac_f32_e32 v98, v89, v45
	v_fmac_f32_e32 v100, v89, v47
	v_fmac_f32_e32 v98, v80, v47
	v_fmac_f32_e32 v100, v80, v51
	v_fmac_f32_e32 v98, v87, v51
	v_fmac_f32_e32 v100, v87, v53
	v_fmac_f32_e32 v98, v79, v53
	v_fmac_f32_e32 v100, v79, v55
	v_fmac_f32_e32 v98, v85, v55
	v_fmac_f32_e32 v100, v85, v57
	v_fmac_f32_e32 v98, v78, v57
	v_fmac_f32_e32 v100, v78, v59
	v_fmac_f32_e32 v98, v83, v59
	v_fmac_f32_e32 v100, v83, v61
	v_fmac_f32_e32 v98, v77, v61
	v_fmac_f32_e32 v100, v77, v63
	v_fmac_f32_e32 v98, v81, v63
	v_fmac_f32_e32 v100, v81, v65
	v_fmac_f32_e32 v98, v48, v65
	v_fmac_f32_e32 v100, v48, v67
	v_fmac_f32_e32 v98, v37, v67
	v_fmac_f32_e32 v100, v37, v69
	v_fmac_f32_e32 v98, v2, v69
	v_fmac_f32_e32 v100, v2, v71
	v_fmac_f32_e32 v98, v4, v71
	v_fmac_f32_e32 v100, v4, v73
	v_fmac_f32_e32 v98, v6, v73
	ds_write2st64_b32 v15, v100, v98 offset0:16 offset1:24
	v_fma_f32 v98, v103, v0, v107
	v_fmac_f32_e32 v98, v96, v1
	v_fma_f32 v96, v96, v0, v107
	v_fmac_f32_e32 v96, v102, v1
	v_fmac_f32_e32 v98, v102, v3
	v_fmac_f32_e32 v96, v94, v3
	v_fmac_f32_e32 v98, v94, v5
	v_fmac_f32_e32 v96, v101, v5
	v_fmac_f32_e32 v98, v101, v7
	v_fmac_f32_e32 v96, v92, v7
	v_fmac_f32_e32 v98, v92, v9
	v_fmac_f32_e32 v96, v99, v9
	v_fmac_f32_e32 v98, v99, v11
	v_fmac_f32_e32 v96, v90, v11
	v_fmac_f32_e32 v98, v90, v23
	v_fmac_f32_e32 v96, v97, v23
	v_fmac_f32_e32 v98, v97, v25
	v_fmac_f32_e32 v96, v88, v25
	v_fmac_f32_e32 v98, v88, v27
	v_fmac_f32_e32 v96, v95, v27
	v_fmac_f32_e32 v98, v95, v29
	v_fmac_f32_e32 v96, v86, v29
	v_fmac_f32_e32 v98, v86, v31
	v_fmac_f32_e32 v96, v93, v31
	v_fmac_f32_e32 v98, v93, v33
	v_fmac_f32_e32 v96, v84, v33
	v_fmac_f32_e32 v98, v84, v35
	v_fmac_f32_e32 v96, v91, v35
	v_fmac_f32_e32 v98, v91, v39
	v_fmac_f32_e32 v96, v82, v39
	v_fmac_f32_e32 v98, v82, v41
	v_fmac_f32_e32 v96, v89, v41
	v_fmac_f32_e32 v98, v89, v43
	v_fmac_f32_e32 v96, v80, v43
	v_fmac_f32_e32 v98, v80, v45
	v_fmac_f32_e32 v96, v87, v45
	v_fmac_f32_e32 v98, v87, v47
	v_fmac_f32_e32 v96, v79, v47
	v_fmac_f32_e32 v98, v79, v51
	v_fmac_f32_e32 v96, v85, v51
	v_fmac_f32_e32 v98, v85, v53
	v_fmac_f32_e32 v96, v78, v53
	v_fmac_f32_e32 v98, v78, v55
	v_fmac_f32_e32 v96, v83, v55
	v_fmac_f32_e32 v98, v83, v57
	v_fmac_f32_e32 v96, v77, v57
	v_fmac_f32_e32 v98, v77, v59
	v_fmac_f32_e32 v96, v81, v59
	v_fmac_f32_e32 v98, v81, v61
	v_fmac_f32_e32 v96, v48, v61
	v_fmac_f32_e32 v98, v48, v63
	v_fmac_f32_e32 v96, v37, v63
	v_fmac_f32_e32 v98, v37, v65
	v_fmac_f32_e32 v96, v2, v65
	v_fmac_f32_e32 v98, v2, v67
	v_fmac_f32_e32 v96, v4, v67
	v_fmac_f32_e32 v98, v4, v69
	v_fmac_f32_e32 v96, v6, v69
	v_fmac_f32_e32 v98, v6, v71
	v_fmac_f32_e32 v96, v8, v71
	v_fmac_f32_e32 v98, v8, v73
	v_fmac_f32_e32 v96, v10, v73
	ds_write2st64_b32 v15, v98, v96 offset0:32 offset1:40
	v_fma_f32 v96, v102, v0, v107
	v_fmac_f32_e32 v96, v94, v1
	v_fma_f32 v94, v94, v0, v107
	v_fmac_f32_e32 v94, v101, v1
	v_fmac_f32_e32 v96, v101, v3
	v_fmac_f32_e32 v94, v92, v3
	v_fmac_f32_e32 v96, v92, v5
	v_fmac_f32_e32 v94, v99, v5
	v_fmac_f32_e32 v96, v99, v7
	v_fmac_f32_e32 v94, v90, v7
	v_fmac_f32_e32 v96, v90, v9
	v_fmac_f32_e32 v94, v97, v9
	v_fmac_f32_e32 v96, v97, v11
	v_fmac_f32_e32 v94, v88, v11
	v_fmac_f32_e32 v96, v88, v23
	v_fmac_f32_e32 v94, v95, v23
	v_fmac_f32_e32 v96, v95, v25
	v_fmac_f32_e32 v94, v86, v25
	v_fmac_f32_e32 v96, v86, v27
	v_fmac_f32_e32 v94, v93, v27
	v_fmac_f32_e32 v96, v93, v29
	v_fmac_f32_e32 v94, v84, v29
	v_fmac_f32_e32 v96, v84, v31
	v_fmac_f32_e32 v94, v91, v31
	v_fmac_f32_e32 v96, v91, v33
	v_fmac_f32_e32 v94, v82, v33
	v_fmac_f32_e32 v96, v82, v35
	v_fmac_f32_e32 v94, v89, v35
	v_fmac_f32_e32 v96, v89, v39
	v_fmac_f32_e32 v94, v80, v39
	v_fmac_f32_e32 v96, v80, v41
	v_fmac_f32_e32 v94, v87, v41
	v_fmac_f32_e32 v96, v87, v43
	v_fmac_f32_e32 v94, v79, v43
	v_fmac_f32_e32 v96, v79, v45
	v_fmac_f32_e32 v94, v85, v45
	v_fmac_f32_e32 v96, v85, v47
	v_fmac_f32_e32 v94, v78, v47
	v_fmac_f32_e32 v96, v78, v51
	v_fmac_f32_e32 v94, v83, v51
	v_fmac_f32_e32 v96, v83, v53
	v_fmac_f32_e32 v94, v77, v53
	v_fmac_f32_e32 v96, v77, v55
	v_fmac_f32_e32 v94, v81, v55
	v_fmac_f32_e32 v96, v81, v57
	v_fmac_f32_e32 v94, v48, v57
	v_fmac_f32_e32 v96, v48, v59
	v_fmac_f32_e32 v94, v37, v59
	v_fmac_f32_e32 v96, v37, v61
	v_fmac_f32_e32 v94, v2, v61
	v_fmac_f32_e32 v96, v2, v63
	v_fmac_f32_e32 v94, v4, v63
	v_fmac_f32_e32 v96, v4, v65
	v_fmac_f32_e32 v94, v6, v65
	v_fmac_f32_e32 v96, v6, v67
	v_fmac_f32_e32 v94, v8, v67
	v_fmac_f32_e32 v96, v8, v69
	v_fmac_f32_e32 v94, v10, v69
	v_fmac_f32_e32 v96, v10, v71
	v_fmac_f32_e32 v94, v22, v71
	v_fmac_f32_e32 v96, v22, v73
	v_fmac_f32_e32 v94, v24, v73
	ds_write2st64_b32 v15, v96, v94 offset0:48 offset1:56
	v_fma_f32 v94, v101, v0, v107
	v_fmac_f32_e32 v94, v92, v1
	v_fma_f32 v92, v92, v0, v107
	v_fmac_f32_e32 v92, v99, v1
	v_fmac_f32_e32 v94, v99, v3
	v_fmac_f32_e32 v92, v90, v3
	v_fmac_f32_e32 v94, v90, v5
	v_fmac_f32_e32 v92, v97, v5
	v_fmac_f32_e32 v94, v97, v7
	v_fmac_f32_e32 v92, v88, v7
	v_fmac_f32_e32 v94, v88, v9
	v_fmac_f32_e32 v92, v95, v9
	v_fmac_f32_e32 v94, v95, v11
	v_fmac_f32_e32 v92, v86, v11
	v_fmac_f32_e32 v94, v86, v23
	v_fmac_f32_e32 v92, v93, v23
	v_fmac_f32_e32 v94, v93, v25
	v_fmac_f32_e32 v92, v84, v25
	v_fmac_f32_e32 v94, v84, v27
	v_fmac_f32_e32 v92, v91, v27
	v_fmac_f32_e32 v94, v91, v29
	v_fmac_f32_e32 v92, v82, v29
	v_fmac_f32_e32 v94, v82, v31
	v_fmac_f32_e32 v92, v89, v31
	v_fmac_f32_e32 v94, v89, v33
	v_fmac_f32_e32 v92, v80, v33
	v_fmac_f32_e32 v94, v80, v35
	v_fmac_f32_e32 v92, v87, v35
	v_fmac_f32_e32 v94, v87, v39
	v_fmac_f32_e32 v92, v79, v39
	v_fmac_f32_e32 v94, v79, v41
	v_fmac_f32_e32 v92, v85, v41
	v_fmac_f32_e32 v94, v85, v43
	v_fmac_f32_e32 v92, v78, v43
	v_fmac_f32_e32 v94, v78, v45
	v_fmac_f32_e32 v92, v83, v45
	v_fmac_f32_e32 v94, v83, v47
	v_fmac_f32_e32 v92, v77, v47
	v_fmac_f32_e32 v94, v77, v51
	v_fmac_f32_e32 v92, v81, v51
	v_fmac_f32_e32 v94, v81, v53
	v_fmac_f32_e32 v92, v48, v53
	v_fmac_f32_e32 v94, v48, v55
	v_fmac_f32_e32 v92, v37, v55
	v_fmac_f32_e32 v94, v37, v57
	v_fmac_f32_e32 v92, v2, v57
	v_fmac_f32_e32 v94, v2, v59
	v_fmac_f32_e32 v92, v4, v59
	v_fmac_f32_e32 v94, v4, v61
	v_fmac_f32_e32 v92, v6, v61
	v_fmac_f32_e32 v94, v6, v63
	v_fmac_f32_e32 v92, v8, v63
	v_fmac_f32_e32 v94, v8, v65
	v_fmac_f32_e32 v92, v10, v65
	v_fmac_f32_e32 v94, v10, v67
	v_fmac_f32_e32 v92, v22, v67
	v_fmac_f32_e32 v94, v22, v69
	v_fmac_f32_e32 v92, v24, v69
	v_fmac_f32_e32 v94, v24, v71
	v_fmac_f32_e32 v92, v26, v71
	v_fmac_f32_e32 v94, v26, v73
	v_fmac_f32_e32 v92, v28, v73
	ds_write2st64_b32 v15, v94, v92 offset0:64 offset1:72
	v_fma_f32 v92, v99, v0, v107
	v_fmac_f32_e32 v92, v90, v1
	v_fma_f32 v90, v90, v0, v107
	v_fmac_f32_e32 v90, v97, v1
	v_fmac_f32_e32 v92, v97, v3
	v_fmac_f32_e32 v90, v88, v3
	v_fmac_f32_e32 v92, v88, v5
	v_fmac_f32_e32 v90, v95, v5
	v_fmac_f32_e32 v92, v95, v7
	v_fmac_f32_e32 v90, v86, v7
	v_fmac_f32_e32 v92, v86, v9
	v_fmac_f32_e32 v90, v93, v9
	v_fmac_f32_e32 v92, v93, v11
	v_fmac_f32_e32 v90, v84, v11
	v_fmac_f32_e32 v92, v84, v23
	v_fmac_f32_e32 v90, v91, v23
	v_fmac_f32_e32 v92, v91, v25
	v_fmac_f32_e32 v90, v82, v25
	v_fmac_f32_e32 v92, v82, v27
	v_fmac_f32_e32 v90, v89, v27
	v_fmac_f32_e32 v92, v89, v29
	v_fmac_f32_e32 v90, v80, v29
	v_fmac_f32_e32 v92, v80, v31
	v_fmac_f32_e32 v90, v87, v31
	v_fmac_f32_e32 v92, v87, v33
	v_fmac_f32_e32 v90, v79, v33
	v_fmac_f32_e32 v92, v79, v35
	v_fmac_f32_e32 v90, v85, v35
	v_fmac_f32_e32 v92, v85, v39
	v_fmac_f32_e32 v90, v78, v39
	v_fmac_f32_e32 v92, v78, v41
	v_fmac_f32_e32 v90, v83, v41
	v_fmac_f32_e32 v92, v83, v43
	v_fmac_f32_e32 v90, v77, v43
	v_fmac_f32_e32 v92, v77, v45
	v_fmac_f32_e32 v90, v81, v45
	v_fmac_f32_e32 v92, v81, v47
	v_fmac_f32_e32 v90, v48, v47
	v_fmac_f32_e32 v92, v48, v51
	v_fmac_f32_e32 v90, v37, v51
	v_fmac_f32_e32 v92, v37, v53
	v_fmac_f32_e32 v90, v2, v53
	v_fmac_f32_e32 v92, v2, v55
	v_fmac_f32_e32 v90, v4, v55
	v_fmac_f32_e32 v92, v4, v57
	v_fmac_f32_e32 v90, v6, v57
	v_fmac_f32_e32 v92, v6, v59
	v_fmac_f32_e32 v90, v8, v59
	v_fmac_f32_e32 v92, v8, v61
	v_fmac_f32_e32 v90, v10, v61
	v_fmac_f32_e32 v92, v10, v63
	v_fmac_f32_e32 v90, v22, v63
	v_fmac_f32_e32 v92, v22, v65
	v_fmac_f32_e32 v90, v24, v65
	v_fmac_f32_e32 v92, v24, v67
	v_fmac_f32_e32 v90, v26, v67
	v_fmac_f32_e32 v92, v26, v69
	v_fmac_f32_e32 v90, v28, v69
	v_fmac_f32_e32 v92, v28, v71
	v_fmac_f32_e32 v90, v30, v71
	v_fmac_f32_e32 v92, v30, v73
	v_fmac_f32_e32 v90, v32, v73
	ds_write2st64_b32 v15, v92, v90 offset0:80 offset1:88
	v_fma_f32 v90, v97, v0, v107
	v_fmac_f32_e32 v90, v88, v1
	v_fma_f32 v88, v88, v0, v107
	v_fmac_f32_e32 v88, v95, v1
	v_fmac_f32_e32 v90, v95, v3
	v_fmac_f32_e32 v88, v86, v3
	v_fmac_f32_e32 v90, v86, v5
	v_fmac_f32_e32 v88, v93, v5
	v_fmac_f32_e32 v90, v93, v7
	v_fmac_f32_e32 v88, v84, v7
	v_fmac_f32_e32 v90, v84, v9
	v_fmac_f32_e32 v88, v91, v9
	v_fmac_f32_e32 v90, v91, v11
	v_fmac_f32_e32 v88, v82, v11
	v_fmac_f32_e32 v90, v82, v23
	v_fmac_f32_e32 v88, v89, v23
	v_fmac_f32_e32 v90, v89, v25
	v_fmac_f32_e32 v88, v80, v25
	v_fmac_f32_e32 v90, v80, v27
	v_fmac_f32_e32 v88, v87, v27
	v_fmac_f32_e32 v90, v87, v29
	v_fmac_f32_e32 v88, v79, v29
	v_fmac_f32_e32 v90, v79, v31
	v_fmac_f32_e32 v88, v85, v31
	v_fmac_f32_e32 v90, v85, v33
	v_fmac_f32_e32 v88, v78, v33
	v_fmac_f32_e32 v90, v78, v35
	v_fmac_f32_e32 v88, v83, v35
	v_fmac_f32_e32 v90, v83, v39
	v_fmac_f32_e32 v88, v77, v39
	v_fmac_f32_e32 v90, v77, v41
	v_fmac_f32_e32 v88, v81, v41
	v_fmac_f32_e32 v90, v81, v43
	v_fmac_f32_e32 v88, v48, v43
	v_fmac_f32_e32 v90, v48, v45
	v_fmac_f32_e32 v88, v37, v45
	v_fmac_f32_e32 v90, v37, v47
	v_fmac_f32_e32 v88, v2, v47
	v_fmac_f32_e32 v90, v2, v51
	v_fmac_f32_e32 v88, v4, v51
	v_fmac_f32_e32 v90, v4, v53
	v_fmac_f32_e32 v88, v6, v53
	v_fmac_f32_e32 v90, v6, v55
	v_fmac_f32_e32 v88, v8, v55
	v_fmac_f32_e32 v90, v8, v57
	v_fmac_f32_e32 v88, v10, v57
	v_fmac_f32_e32 v90, v10, v59
	v_fmac_f32_e32 v88, v22, v59
	v_fmac_f32_e32 v90, v22, v61
	v_fmac_f32_e32 v88, v24, v61
	v_fmac_f32_e32 v90, v24, v63
	v_fmac_f32_e32 v88, v26, v63
	v_fmac_f32_e32 v90, v26, v65
	v_fmac_f32_e32 v88, v28, v65
	v_fmac_f32_e32 v90, v28, v67
	v_fmac_f32_e32 v88, v30, v67
	v_fmac_f32_e32 v90, v30, v69
	v_fmac_f32_e32 v88, v32, v69
	v_fmac_f32_e32 v90, v32, v71
	v_fmac_f32_e32 v88, v34, v71
	v_fmac_f32_e32 v90, v34, v73
	v_fmac_f32_e32 v88, v36, v73
	ds_write2st64_b32 v15, v90, v88 offset0:96 offset1:104
	v_fma_f32 v88, v95, v0, v107
	v_fmac_f32_e32 v88, v86, v1
	v_fma_f32 v86, v86, v0, v107
	v_fmac_f32_e32 v86, v93, v1
	v_fmac_f32_e32 v88, v93, v3
	v_fmac_f32_e32 v86, v84, v3
	v_fmac_f32_e32 v88, v84, v5
	v_fmac_f32_e32 v86, v91, v5
	v_fmac_f32_e32 v88, v91, v7
	v_fmac_f32_e32 v86, v82, v7
	v_fmac_f32_e32 v88, v82, v9
	v_fmac_f32_e32 v86, v89, v9
	v_fmac_f32_e32 v88, v89, v11
	v_fmac_f32_e32 v86, v80, v11
	v_fmac_f32_e32 v88, v80, v23
	v_fmac_f32_e32 v86, v87, v23
	v_fmac_f32_e32 v88, v87, v25
	v_fmac_f32_e32 v86, v79, v25
	v_fmac_f32_e32 v88, v79, v27
	v_fmac_f32_e32 v86, v85, v27
	v_fmac_f32_e32 v88, v85, v29
	v_fmac_f32_e32 v86, v78, v29
	v_fmac_f32_e32 v88, v78, v31
	v_fmac_f32_e32 v86, v83, v31
	v_fmac_f32_e32 v88, v83, v33
	v_fmac_f32_e32 v86, v77, v33
	v_fmac_f32_e32 v88, v77, v35
	v_fmac_f32_e32 v86, v81, v35
	v_fmac_f32_e32 v88, v81, v39
	v_fmac_f32_e32 v86, v48, v39
	v_fmac_f32_e32 v88, v48, v41
	v_fmac_f32_e32 v86, v37, v41
	v_fmac_f32_e32 v88, v37, v43
	v_fmac_f32_e32 v86, v2, v43
	v_fmac_f32_e32 v88, v2, v45
	v_fmac_f32_e32 v86, v4, v45
	v_fmac_f32_e32 v88, v4, v47
	v_fmac_f32_e32 v86, v6, v47
	v_fmac_f32_e32 v88, v6, v51
	v_fmac_f32_e32 v86, v8, v51
	v_fmac_f32_e32 v88, v8, v53
	v_fmac_f32_e32 v86, v10, v53
	v_fmac_f32_e32 v88, v10, v55
	v_fmac_f32_e32 v86, v22, v55
	v_fmac_f32_e32 v88, v22, v57
	v_fmac_f32_e32 v86, v24, v57
	v_fmac_f32_e32 v88, v24, v59
	v_fmac_f32_e32 v86, v26, v59
	v_fmac_f32_e32 v88, v26, v61
	v_fmac_f32_e32 v86, v28, v61
	v_fmac_f32_e32 v88, v28, v63
	v_fmac_f32_e32 v86, v30, v63
	v_fmac_f32_e32 v88, v30, v65
	v_fmac_f32_e32 v86, v32, v65
	v_fmac_f32_e32 v88, v32, v67
	v_fmac_f32_e32 v86, v34, v67
	v_fmac_f32_e32 v88, v34, v69
	v_fmac_f32_e32 v86, v36, v69
	v_fmac_f32_e32 v88, v36, v71
	v_fmac_f32_e32 v86, v38, v71
	v_fmac_f32_e32 v88, v38, v73
	v_fmac_f32_e32 v86, v40, v73
	ds_write2st64_b32 v15, v88, v86 offset0:112 offset1:120
	v_fma_f32 v86, v93, v0, v107
	v_fmac_f32_e32 v86, v84, v1
	v_fma_f32 v84, v84, v0, v107
	v_fmac_f32_e32 v84, v91, v1
	v_fmac_f32_e32 v86, v91, v3
	v_fmac_f32_e32 v84, v82, v3
	v_fmac_f32_e32 v86, v82, v5
	v_fmac_f32_e32 v84, v89, v5
	v_fmac_f32_e32 v86, v89, v7
	v_fmac_f32_e32 v84, v80, v7
	v_fmac_f32_e32 v86, v80, v9
	v_fmac_f32_e32 v84, v87, v9
	v_fmac_f32_e32 v86, v87, v11
	v_fmac_f32_e32 v84, v79, v11
	v_fmac_f32_e32 v86, v79, v23
	v_fmac_f32_e32 v84, v85, v23
	v_fmac_f32_e32 v86, v85, v25
	v_fmac_f32_e32 v84, v78, v25
	v_fmac_f32_e32 v86, v78, v27
	v_fmac_f32_e32 v84, v83, v27
	v_fmac_f32_e32 v86, v83, v29
	v_fmac_f32_e32 v84, v77, v29
	v_fmac_f32_e32 v86, v77, v31
	v_fmac_f32_e32 v84, v81, v31
	v_fmac_f32_e32 v86, v81, v33
	v_fmac_f32_e32 v84, v48, v33
	v_fmac_f32_e32 v86, v48, v35
	v_fmac_f32_e32 v84, v37, v35
	v_fmac_f32_e32 v86, v37, v39
	v_fmac_f32_e32 v84, v2, v39
	v_fmac_f32_e32 v86, v2, v41
	v_fmac_f32_e32 v84, v4, v41
	v_fmac_f32_e32 v86, v4, v43
	v_fmac_f32_e32 v84, v6, v43
	v_fmac_f32_e32 v86, v6, v45
	v_fmac_f32_e32 v84, v8, v45
	v_fmac_f32_e32 v86, v8, v47
	v_fmac_f32_e32 v84, v10, v47
	v_fmac_f32_e32 v86, v10, v51
	v_fmac_f32_e32 v84, v22, v51
	v_fmac_f32_e32 v86, v22, v53
	v_fmac_f32_e32 v84, v24, v53
	v_fmac_f32_e32 v86, v24, v55
	v_fmac_f32_e32 v84, v26, v55
	v_fmac_f32_e32 v86, v26, v57
	v_fmac_f32_e32 v84, v28, v57
	v_fmac_f32_e32 v86, v28, v59
	v_fmac_f32_e32 v84, v30, v59
	v_fmac_f32_e32 v86, v30, v61
	v_fmac_f32_e32 v84, v32, v61
	v_fmac_f32_e32 v86, v32, v63
	v_fmac_f32_e32 v84, v34, v63
	v_fmac_f32_e32 v86, v34, v65
	v_fmac_f32_e32 v84, v36, v65
	v_fmac_f32_e32 v86, v36, v67
	v_fmac_f32_e32 v84, v38, v67
	v_fmac_f32_e32 v86, v38, v69
	v_fmac_f32_e32 v84, v40, v69
	v_fmac_f32_e32 v86, v40, v71
	v_fmac_f32_e32 v84, v42, v71
	v_fmac_f32_e32 v86, v42, v73
	v_fmac_f32_e32 v84, v44, v73
	ds_write2st64_b32 v15, v86, v84 offset0:128 offset1:136
	v_fma_f32 v84, v91, v0, v107
	v_fmac_f32_e32 v84, v82, v1
	v_fma_f32 v82, v82, v0, v107
	v_fmac_f32_e32 v82, v89, v1
	v_fmac_f32_e32 v84, v89, v3
	v_fmac_f32_e32 v82, v80, v3
	v_fmac_f32_e32 v84, v80, v5
	v_fmac_f32_e32 v82, v87, v5
	v_fmac_f32_e32 v84, v87, v7
	v_fmac_f32_e32 v82, v79, v7
	v_fmac_f32_e32 v84, v79, v9
	v_fmac_f32_e32 v82, v85, v9
	v_fmac_f32_e32 v84, v85, v11
	v_fmac_f32_e32 v82, v78, v11
	v_fmac_f32_e32 v84, v78, v23
	v_fmac_f32_e32 v82, v83, v23
	v_fmac_f32_e32 v84, v83, v25
	v_fmac_f32_e32 v82, v77, v25
	v_fmac_f32_e32 v84, v77, v27
	v_fmac_f32_e32 v82, v81, v27
	v_fmac_f32_e32 v84, v81, v29
	v_fmac_f32_e32 v82, v48, v29
	v_fmac_f32_e32 v84, v48, v31
	v_fmac_f32_e32 v82, v37, v31
	v_fmac_f32_e32 v84, v37, v33
	v_fmac_f32_e32 v82, v2, v33
	v_fmac_f32_e32 v84, v2, v35
	v_fmac_f32_e32 v82, v4, v35
	v_fmac_f32_e32 v84, v4, v39
	v_fmac_f32_e32 v82, v6, v39
	v_fmac_f32_e32 v84, v6, v41
	v_fmac_f32_e32 v82, v8, v41
	v_fmac_f32_e32 v84, v8, v43
	v_fmac_f32_e32 v82, v10, v43
	v_fmac_f32_e32 v84, v10, v45
	v_fmac_f32_e32 v82, v22, v45
	v_fmac_f32_e32 v84, v22, v47
	v_fmac_f32_e32 v82, v24, v47
	v_fmac_f32_e32 v84, v24, v51
	v_fmac_f32_e32 v82, v26, v51
	v_fmac_f32_e32 v84, v26, v53
	v_fmac_f32_e32 v82, v28, v53
	v_fmac_f32_e32 v84, v28, v55
	v_fmac_f32_e32 v82, v30, v55
	v_fmac_f32_e32 v84, v30, v57
	v_fmac_f32_e32 v82, v32, v57
	v_fmac_f32_e32 v84, v32, v59
	v_fmac_f32_e32 v82, v34, v59
	v_fmac_f32_e32 v84, v34, v61
	v_fmac_f32_e32 v82, v36, v61
	v_fmac_f32_e32 v84, v36, v63
	v_fmac_f32_e32 v82, v38, v63
	v_fmac_f32_e32 v84, v38, v65
	v_fmac_f32_e32 v82, v40, v65
	v_fmac_f32_e32 v84, v40, v67
	v_fmac_f32_e32 v82, v42, v67
	v_fmac_f32_e32 v84, v42, v69
	v_fmac_f32_e32 v82, v44, v69
	v_fmac_f32_e32 v84, v44, v71
	v_fmac_f32_e32 v82, v46, v71
	v_fmac_f32_e32 v84, v46, v73
	v_fmac_f32_e32 v82, v50, v73
	ds_write2st64_b32 v15, v84, v82 offset0:144 offset1:152
	v_fma_f32 v82, v89, v0, v107
	v_fmac_f32_e32 v82, v80, v1
	v_fma_f32 v80, v80, v0, v107
	v_fmac_f32_e32 v80, v87, v1
	v_fmac_f32_e32 v82, v87, v3
	v_fmac_f32_e32 v80, v79, v3
	v_fmac_f32_e32 v82, v79, v5
	v_fmac_f32_e32 v80, v85, v5
	v_fmac_f32_e32 v82, v85, v7
	v_fmac_f32_e32 v80, v78, v7
	v_fmac_f32_e32 v82, v78, v9
	v_fmac_f32_e32 v80, v83, v9
	v_fmac_f32_e32 v82, v83, v11
	v_fmac_f32_e32 v80, v77, v11
	v_fmac_f32_e32 v82, v77, v23
	v_fmac_f32_e32 v80, v81, v23
	v_fmac_f32_e32 v82, v81, v25
	v_fmac_f32_e32 v80, v48, v25
	v_fmac_f32_e32 v82, v48, v27
	v_fmac_f32_e32 v80, v37, v27
	v_fmac_f32_e32 v82, v37, v29
	v_fmac_f32_e32 v80, v2, v29
	v_fmac_f32_e32 v82, v2, v31
	v_fmac_f32_e32 v80, v4, v31
	v_fmac_f32_e32 v82, v4, v33
	v_fmac_f32_e32 v80, v6, v33
	v_fmac_f32_e32 v82, v6, v35
	v_fmac_f32_e32 v80, v8, v35
	v_fmac_f32_e32 v82, v8, v39
	v_fmac_f32_e32 v80, v10, v39
	v_fmac_f32_e32 v82, v10, v41
	v_fmac_f32_e32 v80, v22, v41
	v_fmac_f32_e32 v82, v22, v43
	v_fmac_f32_e32 v80, v24, v43
	v_fmac_f32_e32 v82, v24, v45
	v_fmac_f32_e32 v80, v26, v45
	v_fmac_f32_e32 v82, v26, v47
	v_fmac_f32_e32 v80, v28, v47
	v_fmac_f32_e32 v82, v28, v51
	v_fmac_f32_e32 v80, v30, v51
	v_fmac_f32_e32 v82, v30, v53
	v_fmac_f32_e32 v80, v32, v53
	v_fmac_f32_e32 v82, v32, v55
	v_fmac_f32_e32 v80, v34, v55
	v_fmac_f32_e32 v82, v34, v57
	v_fmac_f32_e32 v80, v36, v57
	v_fmac_f32_e32 v82, v36, v59
	v_fmac_f32_e32 v80, v38, v59
	v_fmac_f32_e32 v82, v38, v61
	v_fmac_f32_e32 v80, v40, v61
	v_fmac_f32_e32 v82, v40, v63
	v_fmac_f32_e32 v80, v42, v63
	v_fmac_f32_e32 v82, v42, v65
	v_fmac_f32_e32 v80, v44, v65
	v_fmac_f32_e32 v82, v44, v67
	v_fmac_f32_e32 v80, v46, v67
	v_fmac_f32_e32 v82, v46, v69
	v_fmac_f32_e32 v80, v50, v69
	v_fmac_f32_e32 v82, v50, v71
	v_fmac_f32_e32 v80, v52, v71
	v_fmac_f32_e32 v82, v52, v73
	v_fmac_f32_e32 v80, v54, v73
	ds_write2st64_b32 v15, v82, v80 offset0:160 offset1:168
	v_fma_f32 v80, v87, v0, v107
	v_fmac_f32_e32 v80, v79, v1
	v_fma_f32 v79, v79, v0, v107
	v_fmac_f32_e32 v79, v85, v1
	v_fmac_f32_e32 v80, v85, v3
	v_fmac_f32_e32 v79, v78, v3
	v_fmac_f32_e32 v80, v78, v5
	v_fmac_f32_e32 v79, v83, v5
	v_fmac_f32_e32 v80, v83, v7
	v_fmac_f32_e32 v79, v77, v7
	v_fmac_f32_e32 v80, v77, v9
	v_fmac_f32_e32 v79, v81, v9
	v_fmac_f32_e32 v80, v81, v11
	v_fmac_f32_e32 v79, v48, v11
	v_fmac_f32_e32 v80, v48, v23
	v_fmac_f32_e32 v79, v37, v23
	v_fmac_f32_e32 v80, v37, v25
	v_fmac_f32_e32 v79, v2, v25
	v_fmac_f32_e32 v80, v2, v27
	v_fmac_f32_e32 v79, v4, v27
	v_fmac_f32_e32 v80, v4, v29
	v_fmac_f32_e32 v79, v6, v29
	v_fmac_f32_e32 v80, v6, v31
	v_fmac_f32_e32 v79, v8, v31
	v_fmac_f32_e32 v80, v8, v33
	v_fmac_f32_e32 v79, v10, v33
	v_fmac_f32_e32 v80, v10, v35
	v_fmac_f32_e32 v79, v22, v35
	v_fmac_f32_e32 v80, v22, v39
	v_fmac_f32_e32 v79, v24, v39
	v_fmac_f32_e32 v80, v24, v41
	v_fmac_f32_e32 v79, v26, v41
	v_fmac_f32_e32 v80, v26, v43
	v_fmac_f32_e32 v79, v28, v43
	v_fmac_f32_e32 v80, v28, v45
	v_fmac_f32_e32 v79, v30, v45
	v_fmac_f32_e32 v80, v30, v47
	v_fmac_f32_e32 v79, v32, v47
	v_fmac_f32_e32 v80, v32, v51
	v_fmac_f32_e32 v79, v34, v51
	v_fmac_f32_e32 v80, v34, v53
	v_fmac_f32_e32 v79, v36, v53
	v_fmac_f32_e32 v80, v36, v55
	v_fmac_f32_e32 v79, v38, v55
	v_fmac_f32_e32 v80, v38, v57
	v_fmac_f32_e32 v79, v40, v57
	v_fmac_f32_e32 v80, v40, v59
	v_fmac_f32_e32 v79, v42, v59
	v_fmac_f32_e32 v80, v42, v61
	v_fmac_f32_e32 v79, v44, v61
	v_fmac_f32_e32 v80, v44, v63
	v_fmac_f32_e32 v79, v46, v63
	v_fmac_f32_e32 v80, v46, v65
	v_fmac_f32_e32 v79, v50, v65
	v_fmac_f32_e32 v80, v50, v67
	v_fmac_f32_e32 v79, v52, v67
	v_fmac_f32_e32 v80, v52, v69
	v_fmac_f32_e32 v79, v54, v69
	v_fmac_f32_e32 v80, v54, v71
	v_fmac_f32_e32 v79, v56, v71
	v_fmac_f32_e32 v80, v56, v73
	v_fmac_f32_e32 v79, v58, v73
	ds_write2st64_b32 v15, v80, v79 offset0:176 offset1:184
	v_fma_f32 v79, v85, v0, v107
	v_fmac_f32_e32 v79, v78, v1
	v_fma_f32 v78, v78, v0, v107
	v_fmac_f32_e32 v78, v83, v1
	v_fmac_f32_e32 v79, v83, v3
	v_fmac_f32_e32 v78, v77, v3
	v_fmac_f32_e32 v79, v77, v5
	v_fmac_f32_e32 v78, v81, v5
	v_fmac_f32_e32 v79, v81, v7
	v_fmac_f32_e32 v78, v48, v7
	v_fmac_f32_e32 v79, v48, v9
	v_fmac_f32_e32 v78, v37, v9
	v_fmac_f32_e32 v79, v37, v11
	v_fmac_f32_e32 v78, v2, v11
	v_fmac_f32_e32 v79, v2, v23
	v_fmac_f32_e32 v78, v4, v23
	v_fmac_f32_e32 v79, v4, v25
	v_fmac_f32_e32 v78, v6, v25
	v_fmac_f32_e32 v79, v6, v27
	v_fmac_f32_e32 v78, v8, v27
	v_fmac_f32_e32 v79, v8, v29
	v_fmac_f32_e32 v78, v10, v29
	v_fmac_f32_e32 v79, v10, v31
	v_fmac_f32_e32 v78, v22, v31
	v_fmac_f32_e32 v79, v22, v33
	v_fmac_f32_e32 v78, v24, v33
	v_fmac_f32_e32 v79, v24, v35
	v_fmac_f32_e32 v78, v26, v35
	v_fmac_f32_e32 v79, v26, v39
	v_fmac_f32_e32 v78, v28, v39
	v_fmac_f32_e32 v79, v28, v41
	v_fmac_f32_e32 v78, v30, v41
	v_fmac_f32_e32 v79, v30, v43
	v_fmac_f32_e32 v78, v32, v43
	v_fmac_f32_e32 v79, v32, v45
	v_fmac_f32_e32 v78, v34, v45
	v_fmac_f32_e32 v79, v34, v47
	v_fmac_f32_e32 v78, v36, v47
	v_fmac_f32_e32 v79, v36, v51
	v_fmac_f32_e32 v78, v38, v51
	v_fmac_f32_e32 v79, v38, v53
	v_fmac_f32_e32 v78, v40, v53
	v_fmac_f32_e32 v79, v40, v55
	v_fmac_f32_e32 v78, v42, v55
	v_fmac_f32_e32 v79, v42, v57
	v_fmac_f32_e32 v78, v44, v57
	v_fmac_f32_e32 v79, v44, v59
	v_fmac_f32_e32 v78, v46, v59
	v_fmac_f32_e32 v79, v46, v61
	v_fmac_f32_e32 v78, v50, v61
	v_fmac_f32_e32 v79, v50, v63
	v_fmac_f32_e32 v78, v52, v63
	v_fmac_f32_e32 v79, v52, v65
	v_fmac_f32_e32 v78, v54, v65
	v_fmac_f32_e32 v79, v54, v67
	v_fmac_f32_e32 v78, v56, v67
	v_fmac_f32_e32 v79, v56, v69
	v_fmac_f32_e32 v78, v58, v69
	v_fmac_f32_e32 v79, v58, v71
	v_fmac_f32_e32 v78, v60, v71
	v_fmac_f32_e32 v79, v60, v73
	v_fmac_f32_e32 v78, v62, v73
	ds_write2st64_b32 v15, v79, v78 offset0:192 offset1:200
	v_fma_f32 v78, v83, v0, v107
	v_fmac_f32_e32 v78, v77, v1
	v_fma_f32 v77, v77, v0, v107
	v_fmac_f32_e32 v77, v81, v1
	v_fmac_f32_e32 v78, v81, v3
	v_fmac_f32_e32 v77, v48, v3
	v_fmac_f32_e32 v78, v48, v5
	v_fmac_f32_e32 v77, v37, v5
	v_fmac_f32_e32 v78, v37, v7
	v_fmac_f32_e32 v77, v2, v7
	v_fmac_f32_e32 v78, v2, v9
	v_fmac_f32_e32 v77, v4, v9
	v_fmac_f32_e32 v78, v4, v11
	v_fmac_f32_e32 v77, v6, v11
	v_fmac_f32_e32 v78, v6, v23
	v_fmac_f32_e32 v77, v8, v23
	v_fmac_f32_e32 v78, v8, v25
	v_fmac_f32_e32 v77, v10, v25
	v_fmac_f32_e32 v78, v10, v27
	v_fmac_f32_e32 v77, v22, v27
	v_fmac_f32_e32 v78, v22, v29
	v_fmac_f32_e32 v77, v24, v29
	v_fmac_f32_e32 v78, v24, v31
	v_fmac_f32_e32 v77, v26, v31
	v_fmac_f32_e32 v78, v26, v33
	v_fmac_f32_e32 v77, v28, v33
	v_fmac_f32_e32 v78, v28, v35
	v_fmac_f32_e32 v77, v30, v35
	v_fmac_f32_e32 v78, v30, v39
	v_fmac_f32_e32 v77, v32, v39
	v_fmac_f32_e32 v78, v32, v41
	v_fmac_f32_e32 v77, v34, v41
	v_fmac_f32_e32 v78, v34, v43
	v_fmac_f32_e32 v77, v36, v43
	v_fmac_f32_e32 v78, v36, v45
	v_fmac_f32_e32 v77, v38, v45
	v_fmac_f32_e32 v78, v38, v47
	v_fmac_f32_e32 v77, v40, v47
	v_fmac_f32_e32 v78, v40, v51
	v_fmac_f32_e32 v77, v42, v51
	v_fmac_f32_e32 v78, v42, v53
	v_fmac_f32_e32 v77, v44, v53
	v_fmac_f32_e32 v78, v44, v55
	v_fmac_f32_e32 v77, v46, v55
	v_fmac_f32_e32 v78, v46, v57
	v_fmac_f32_e32 v77, v50, v57
	v_fmac_f32_e32 v78, v50, v59
	v_fmac_f32_e32 v77, v52, v59
	v_fmac_f32_e32 v78, v52, v61
	v_fmac_f32_e32 v77, v54, v61
	v_fmac_f32_e32 v78, v54, v63
	v_fmac_f32_e32 v77, v56, v63
	v_fmac_f32_e32 v78, v56, v65
	v_fmac_f32_e32 v77, v58, v65
	v_fmac_f32_e32 v78, v58, v67
	v_fmac_f32_e32 v77, v60, v67
	v_fmac_f32_e32 v78, v60, v69
	v_fmac_f32_e32 v77, v62, v69
	v_fmac_f32_e32 v78, v62, v71
	v_fmac_f32_e32 v77, v64, v71
	v_fmac_f32_e32 v78, v64, v73
	v_fmac_f32_e32 v77, v66, v73
	ds_write2st64_b32 v15, v78, v77 offset0:208 offset1:216
	v_fma_f32 v77, v81, v0, v107
	v_fmac_f32_e32 v77, v48, v1
	v_fma_f32 v48, v48, v0, v107
	v_fmac_f32_e32 v77, v37, v3
	v_fmac_f32_e32 v48, v37, v1
	v_fma_f32 v37, v37, v0, v107
	v_fmac_f32_e32 v107, v2, v0
	v_fmac_f32_e32 v77, v2, v5
	v_fmac_f32_e32 v48, v2, v3
	v_fmac_f32_e32 v37, v2, v1
	v_fmac_f32_e32 v107, v4, v1
	v_fmac_f32_e32 v77, v4, v7
	v_fmac_f32_e32 v48, v4, v5
	v_fmac_f32_e32 v37, v4, v3
	v_fmac_f32_e32 v107, v6, v3
	v_add_u32_e32 v2, s91, v74
	v_fmac_f32_e32 v77, v6, v9
	v_fmac_f32_e32 v48, v6, v7
	v_fmac_f32_e32 v37, v6, v5
	v_fmac_f32_e32 v107, v8, v5
	v_ashrrev_i32_e32 v3, 31, v2
	v_lshl_or_b32 v6, v2, 4, v75
	v_fmac_f32_e32 v37, v8, v7
	v_fmac_f32_e32 v107, v10, v7
	v_lshl_add_u64 v[0:1], s[44:45], 0, v[2:3]
	v_ashrrev_i32_e32 v7, 31, v6
	v_mad_u64_u32 v[4:5], s[6:7], v0, s8, v[18:19]
	v_lshlrev_b64 v[6:7], 2, v[6:7]
	v_fmac_f32_e32 v77, v8, v11
	v_fmac_f32_e32 v48, v8, v9
	v_fmac_f32_e32 v37, v10, v9
	v_fmac_f32_e32 v107, v22, v9
	v_mad_i32_i24 v5, v1, s8, v5
	v_lshl_add_u64 v[8:9], s[46:47], 0, v[6:7]
	global_load_ushort v3, v[4:5], off offset:768
	global_load_dword v2, v[8:9], off
	v_lshl_add_u64 v[6:7], s[48:49], 0, v[6:7]
	global_load_ushort v4, v[4:5], off offset:800
	v_fmac_f32_e32 v48, v10, v11
	global_load_dword v5, v[6:7], off
	v_fmac_f32_e32 v37, v22, v11
	v_fmac_f32_e32 v107, v24, v11
	v_fmac_f32_e32 v77, v10, v23
	v_fmac_f32_e32 v48, v22, v23
	v_fmac_f32_e32 v37, v24, v23
	v_fmac_f32_e32 v107, v26, v23
	v_fmac_f32_e32 v77, v22, v25
	v_fmac_f32_e32 v48, v24, v25
	v_fmac_f32_e32 v37, v26, v25
	v_fmac_f32_e32 v107, v28, v25
	v_fmac_f32_e32 v77, v24, v27
	v_fmac_f32_e32 v48, v26, v27
	v_fmac_f32_e32 v37, v28, v27
	v_fmac_f32_e32 v107, v30, v27
	v_fmac_f32_e32 v77, v26, v29
	v_fmac_f32_e32 v48, v28, v29
	v_fmac_f32_e32 v37, v30, v29
	v_fmac_f32_e32 v107, v32, v29
	v_fmac_f32_e32 v77, v28, v31
	v_fmac_f32_e32 v48, v30, v31
	v_fmac_f32_e32 v37, v32, v31
	v_fmac_f32_e32 v107, v34, v31
	v_fmac_f32_e32 v77, v30, v33
	v_fmac_f32_e32 v48, v32, v33
	v_fmac_f32_e32 v37, v34, v33
	v_fmac_f32_e32 v107, v36, v33
	v_fmac_f32_e32 v77, v32, v35
	v_fmac_f32_e32 v48, v34, v35
	v_fmac_f32_e32 v37, v36, v35
	v_fmac_f32_e32 v107, v38, v35
	v_fmac_f32_e32 v77, v34, v39
	v_fmac_f32_e32 v48, v36, v39
	v_fmac_f32_e32 v37, v38, v39
	v_fmac_f32_e32 v107, v40, v39
	v_fmac_f32_e32 v77, v36, v41
	v_fmac_f32_e32 v48, v38, v41
	v_fmac_f32_e32 v37, v40, v41
	v_fmac_f32_e32 v107, v42, v41
	v_fmac_f32_e32 v77, v38, v43
	v_fmac_f32_e32 v48, v40, v43
	v_fmac_f32_e32 v37, v42, v43
	v_fmac_f32_e32 v107, v44, v43
	v_fmac_f32_e32 v77, v40, v45
	v_fmac_f32_e32 v48, v42, v45
	v_fmac_f32_e32 v37, v44, v45
	v_fmac_f32_e32 v107, v46, v45
	v_fmac_f32_e32 v77, v42, v47
	v_fmac_f32_e32 v48, v44, v47
	v_fmac_f32_e32 v37, v46, v47
	v_fmac_f32_e32 v107, v50, v47
	v_fmac_f32_e32 v77, v44, v51
	v_fmac_f32_e32 v48, v46, v51
	v_fmac_f32_e32 v37, v50, v51
	v_fmac_f32_e32 v107, v52, v51
	v_fmac_f32_e32 v77, v46, v53
	v_fmac_f32_e32 v48, v50, v53
	v_fmac_f32_e32 v37, v52, v53
	v_fmac_f32_e32 v107, v54, v53
	v_fmac_f32_e32 v77, v50, v55
	v_fmac_f32_e32 v48, v52, v55
	v_fmac_f32_e32 v37, v54, v55
	v_fmac_f32_e32 v107, v56, v55
	v_fmac_f32_e32 v77, v52, v57
	v_fmac_f32_e32 v48, v54, v57
	v_fmac_f32_e32 v37, v56, v57
	v_fmac_f32_e32 v107, v58, v57
	v_fmac_f32_e32 v77, v54, v59
	v_fmac_f32_e32 v48, v56, v59
	v_fmac_f32_e32 v37, v58, v59
	v_fmac_f32_e32 v107, v60, v59
	v_fmac_f32_e32 v77, v56, v61
	v_fmac_f32_e32 v48, v58, v61
	v_fmac_f32_e32 v37, v60, v61
	v_fmac_f32_e32 v107, v62, v61
	s_waitcnt vmcnt(3)
	v_lshlrev_b32_e32 v3, 16, v3
	v_lshlrev_b64 v[0:1], 6, v[0:1]
	v_fmac_f32_e32 v77, v58, v63
	s_waitcnt vmcnt(1)
	v_lshlrev_b32_e32 v4, 16, v4
	v_fmac_f32_e32 v48, v60, v63
	s_waitcnt vmcnt(0)
	v_mul_f32_e32 v6, v5, v4
	v_fma_f32 v6, v2, v3, -v6
	v_mul_f32_e32 v2, v2, v4
	v_fmac_f32_e32 v2, v5, v3
	v_fmac_f32_e32 v37, v62, v63
	v_fmac_f32_e32 v107, v64, v63
	v_cvt_pk_bf16_f32 v6, v6, s0
	v_lshl_add_u64 v[0:1], v[12:13], 0, v[0:1]
	v_cvt_pk_bf16_f32 v2, v2, s0
	v_fmac_f32_e32 v77, v60, v65
	v_fmac_f32_e32 v48, v62, v65
	v_fmac_f32_e32 v37, v64, v65
	v_fmac_f32_e32 v107, v66, v65
	global_store_short v[0:1], v6, off
	global_store_short v[0:1], v2, off offset:8
	v_and_b32_e32 v1, 64, v205
	v_fmac_f32_e32 v77, v62, v67
	v_fmac_f32_e32 v48, v64, v67
	v_fmac_f32_e32 v37, v66, v67
	v_fmac_f32_e32 v107, v68, v67
	v_xor_b32_e32 v0, 16, v205
	v_add_u32_e32 v1, 64, v1
	v_fmac_f32_e32 v77, v64, v69
	v_fmac_f32_e32 v48, v66, v69
	v_fmac_f32_e32 v37, v68, v69
	v_fmac_f32_e32 v107, v70, v69
	v_cmp_lt_i32_e32 vcc, v0, v1
	v_fmac_f32_e32 v77, v66, v71
	v_fmac_f32_e32 v48, v68, v71
	v_fmac_f32_e32 v37, v70, v71
	v_fmac_f32_e32 v107, v72, v71
	v_cndmask_b32_e32 v0, v205, v0, vcc
	v_fmac_f32_e32 v77, v68, v73
	v_fmac_f32_e32 v48, v70, v73
	v_fmac_f32_e32 v37, v72, v73
	v_fmac_f32_e32 v107, v106, v73
	v_lshlrev_b32_e32 v28, 2, v0
	v_add_u32_e32 v0, s63, v76
	ds_write2st64_b32 v15, v77, v48 offset0:224 offset1:232
	ds_write2st64_b32 v15, v37, v107 offset0:240 offset1:248
	s_waitcnt lgkmcnt(0)
	s_barrier
	ds_read_b128 v[8:11], v0
	ds_read_b128 v[0:3], v0 offset:16
	v_lshlrev_b32_e32 v29, 2, v14
	s_add_u32 s6, s24, s62
	s_addc_u32 s7, s45, s64
	s_waitcnt lgkmcnt(1)
	v_add_f32_e32 v4, 0, v8
	v_add_f32_e32 v4, v9, v4
	v_add_f32_e32 v4, v10, v4
	v_add_f32_e32 v4, v11, v4
	s_waitcnt lgkmcnt(0)
	v_add_f32_e32 v4, v0, v4
	v_add_f32_e32 v4, v1, v4
	v_add_f32_e32 v4, v2, v4
	v_add_f32_e32 v4, v3, v4
	s_lshl_b64 s[6:7], s[6:7], 11
	s_add_u32 s6, s2, s6
	v_add_f32_dpp v4, v4, v4 row_mirror row_mask:0xf bank_mask:0xf bound_ctrl:1
	s_addc_u32 s7, s3, s7
	v_lshlrev_b32_e32 v48, 1, v14
	v_add_f32_dpp v4, v4, v4 row_half_mirror row_mask:0xf bank_mask:0xf bound_ctrl:1
	s_mov_b64 s[8:9], 0x7800400
	s_nop 0
	v_add_f32_dpp v4, v4, v4 quad_perm:[1,0,3,2] row_mask:0xf bank_mask:0xf bound_ctrl:1
	s_nop 1
	v_add_f32_dpp v4, v4, v4 quad_perm:[2,3,0,1] row_mask:0xf bank_mask:0xf bound_ctrl:1
	s_waitcnt lgkmcnt(0)
	v_mov_b32_e32 v5, v4
	s_nop 1
	v_permlane16_swap_b32_e32 v4, v5
	v_add_f32_e32 v4, v4, v5
	v_mov_b32_e32 v5, v4
	s_nop 1
	v_permlane32_swap_b32_e32 v4, v5
	v_add_f32_e32 v4, v4, v5
	v_mul_f32_e32 v24, 0x3b000000, v4
	v_pk_add_f32 v[22:23], v[2:3], v[24:25] op_sel_hi:[1,0] neg_lo:[0,1] neg_hi:[0,1]
	v_pk_add_f32 v[26:27], v[0:1], v[24:25] op_sel_hi:[1,0] neg_lo:[0,1] neg_hi:[0,1]
	global_load_dwordx4 v[180:183], v29, s[40:41] offset:16
	global_load_dwordx4 v[184:187], v29, s[40:41]
	global_load_dwordx4 v[188:191], v29, s[50:51] offset:16
	global_load_dwordx4 v[192:195], v29, s[50:51]
	v_pk_add_f32 v[8:9], v[8:9], v[24:25] op_sel_hi:[1,0] neg_lo:[0,1] neg_hi:[0,1]
	v_pk_add_f32 v[10:11], v[10:11], v[24:25] op_sel_hi:[1,0] neg_lo:[0,1] neg_hi:[0,1]
	v_pk_mul_f32 v[24:25], v[8:9], v[8:9]
	v_pk_mul_f32 v[42:43], v[10:11], v[10:11]
	v_add_f32_e32 v24, v24, v25
	v_add_f32_e32 v24, v42, v24
	v_pk_mul_f32 v[40:41], v[26:27], v[26:27]
	v_add_f32_e32 v24, v43, v24
	v_add_f32_e32 v24, v40, v24
	v_pk_mul_f32 v[38:39], v[22:23], v[22:23]
	v_add_f32_e32 v24, v41, v24
	v_add_f32_e32 v24, v38, v24
	v_add_f32_e32 v24, v39, v24
	s_nop 1
	v_add_f32_dpp v24, v24, v24 row_mirror row_mask:0xf bank_mask:0xf bound_ctrl:1
	s_nop 1
	v_add_f32_dpp v24, v24, v24 row_half_mirror row_mask:0xf bank_mask:0xf bound_ctrl:1
	s_nop 1
	v_add_f32_dpp v24, v24, v24 quad_perm:[1,0,3,2] row_mask:0xf bank_mask:0xf bound_ctrl:1
	s_nop 1
	v_add_f32_dpp v24, v24, v24 quad_perm:[2,3,0,1] row_mask:0xf bank_mask:0xf bound_ctrl:1
	s_waitcnt lgkmcnt(0)
	v_mov_b32_e32 v25, v24
	s_nop 1
	v_permlane16_swap_b32_e32 v24, v25
	v_add_f32_e32 v24, v24, v25
	v_mov_b32_e32 v25, v24
	s_nop 1
	v_permlane32_swap_b32_e32 v24, v25
	v_add_f32_e32 v24, v24, v25
	v_fmamk_f32 v24, v24, 0x3b000000, v206
	v_cmp_gt_f32_e32 vcc, s75, v24
	v_mul_f32_e32 v25, 0x4b800000, v24
	s_nop 0
	v_cndmask_b32_e32 v24, v24, v25, vcc
	v_rsq_f32_e32 v24, v24
	s_nop 0
	v_mul_f32_e32 v25, 0x45800000, v24
	v_cndmask_b32_e32 v24, v24, v25, vcc
	v_pk_mul_f32 v[8:9], v[8:9], v[24:25] op_sel_hi:[1,0]
	s_waitcnt vmcnt(0)
	v_pk_fma_f32 v[8:9], v[184:185], v[8:9], v[192:193]
	s_nop 0
	v_mul_f32_e32 v25, 0xbfb8aa3b, v8
	v_exp_f32_e32 v25, v25
	s_nop 0
	v_add_f32_e32 v25, 1.0, v25
	v_rcp_f32_e32 v30, v25
	v_mul_f32_e32 v25, 0xbfb8aa3b, v9
	v_exp_f32_e32 v25, v25
	s_nop 0
	v_add_f32_e32 v25, 1.0, v25
	v_pk_mul_f32 v[10:11], v[10:11], v[24:25] op_sel_hi:[1,0]
	v_rcp_f32_e32 v31, v25
	v_pk_fma_f32 v[10:11], v[186:187], v[10:11], v[194:195]
	v_pk_mul_f32 v[8:9], v[8:9], v[30:31]
	v_mul_f32_e32 v25, 0xbfb8aa3b, v10
	v_exp_f32_e32 v25, v25
	s_nop 0
	v_add_f32_e32 v25, 1.0, v25
	v_rcp_f32_e32 v30, v25
	v_mul_f32_e32 v25, 0xbfb8aa3b, v11
	v_exp_f32_e32 v25, v25
	s_nop 0
	v_add_f32_e32 v25, 1.0, v25
	v_pk_mul_f32 v[26:27], v[26:27], v[24:25] op_sel_hi:[1,0]
	v_rcp_f32_e32 v31, v25
	v_pk_fma_f32 v[0:1], v[180:181], v[26:27], v[188:189]
	v_pk_mul_f32 v[10:11], v[10:11], v[30:31]
	v_mul_f32_e32 v4, 0xbfb8aa3b, v0
	v_mul_f32_e32 v5, 0xbfb8aa3b, v1
	v_exp_f32_e32 v4, v4
	v_exp_f32_e32 v5, v5
	v_add_f32_e32 v4, 1.0, v4
	v_add_f32_e32 v5, 1.0, v5
	v_rcp_f32_e32 v4, v4
	v_rcp_f32_e32 v5, v5
	s_nop 0
	v_pk_mul_f32 v[4:5], v[0:1], v[4:5]
	v_pk_mul_f32 v[0:1], v[22:23], v[24:25] op_sel_hi:[1,0]
	s_nop 0
	v_pk_fma_f32 v[0:1], v[0:1], v[182:183], v[190:191]
	s_nop 0
	v_mul_f32_e32 v2, 0xbfb8aa3b, v0
	v_mul_f32_e32 v3, 0xbfb8aa3b, v1
	v_exp_f32_e32 v2, v2
	v_exp_f32_e32 v3, v3
	v_add_f32_e32 v2, 1.0, v2
	v_add_f32_e32 v3, 1.0, v3
	v_rcp_f32_e32 v2, v2
	v_rcp_f32_e32 v3, v3
	s_nop 0
	v_pk_mul_f32 v[6:7], v[0:1], v[2:3]
	v_cvt_pk_bf16_f32 v0, v8, v9
	v_cvt_pk_bf16_f32 v2, v4, v5
	v_lshl_add_u64 v[4:5], s[6:7], 0, v[48:49]
	v_cvt_pk_bf16_f32 v1, v10, v11
	v_cvt_pk_bf16_f32 v3, v6, v7
	v_lshl_add_u64 v[4:5], v[4:5], 0, s[8:9]
	global_store_dwordx4 v[4:5], v[0:3], off
	s_nop 1
	v_add_u32_e32 v0, s66, v76
	ds_read_b128 v[8:11], v0
	ds_read_b128 v[0:3], v0 offset:16
	s_add_u32 s6, s24, s65
	s_addc_u32 s7, s45, s67
	s_lshl_b64 s[6:7], s[6:7], 11
	s_waitcnt lgkmcnt(1)
	v_add_f32_e32 v4, 0, v8
	v_add_f32_e32 v4, v9, v4
	v_add_f32_e32 v4, v10, v4
	v_add_f32_e32 v4, v11, v4
	s_waitcnt lgkmcnt(0)
	v_add_f32_e32 v4, v0, v4
	v_add_f32_e32 v4, v1, v4
	v_add_f32_e32 v4, v2, v4
	v_add_f32_e32 v4, v3, v4
	s_add_u32 s6, s2, s6
	s_addc_u32 s7, s3, s7
	v_add_f32_dpp v4, v4, v4 row_mirror row_mask:0xf bank_mask:0xf bound_ctrl:1
	s_nop 1
	v_add_f32_dpp v4, v4, v4 row_half_mirror row_mask:0xf bank_mask:0xf bound_ctrl:1
	s_nop 1
	v_add_f32_dpp v4, v4, v4 quad_perm:[1,0,3,2] row_mask:0xf bank_mask:0xf bound_ctrl:1
	s_nop 1
	v_add_f32_dpp v4, v4, v4 quad_perm:[2,3,0,1] row_mask:0xf bank_mask:0xf bound_ctrl:1
	s_waitcnt lgkmcnt(0)
	v_mov_b32_e32 v5, v4
	s_nop 1
	v_permlane16_swap_b32_e32 v4, v5
	v_add_f32_e32 v4, v4, v5
	v_mov_b32_e32 v5, v4
	s_nop 1
	v_permlane32_swap_b32_e32 v4, v5
	v_add_f32_e32 v4, v4, v5
	v_mul_f32_e32 v26, 0x3b000000, v4
	v_pk_add_f32 v[22:23], v[2:3], v[26:27] op_sel_hi:[1,0] neg_lo:[0,1] neg_hi:[0,1]
	v_pk_add_f32 v[24:25], v[0:1], v[26:27] op_sel_hi:[1,0] neg_lo:[0,1] neg_hi:[0,1]
	v_pk_add_f32 v[8:9], v[8:9], v[26:27] op_sel_hi:[1,0] neg_lo:[0,1] neg_hi:[0,1]
	v_pk_add_f32 v[10:11], v[10:11], v[26:27] op_sel_hi:[1,0] neg_lo:[0,1] neg_hi:[0,1]
	v_pk_mul_f32 v[26:27], v[8:9], v[8:9]
	v_pk_mul_f32 v[42:43], v[10:11], v[10:11]
	v_add_f32_e32 v26, v26, v27
	v_add_f32_e32 v26, v42, v26
	v_pk_mul_f32 v[40:41], v[24:25], v[24:25]
	v_add_f32_e32 v26, v43, v26
	v_add_f32_e32 v26, v40, v26
	v_pk_mul_f32 v[38:39], v[22:23], v[22:23]
	v_add_f32_e32 v26, v41, v26
	v_add_f32_e32 v26, v38, v26
	v_add_f32_e32 v26, v39, v26
	s_nop 1
	v_add_f32_dpp v26, v26, v26 row_mirror row_mask:0xf bank_mask:0xf bound_ctrl:1
	s_nop 1
	v_add_f32_dpp v26, v26, v26 row_half_mirror row_mask:0xf bank_mask:0xf bound_ctrl:1
	s_nop 1
	v_add_f32_dpp v26, v26, v26 quad_perm:[1,0,3,2] row_mask:0xf bank_mask:0xf bound_ctrl:1
	s_nop 1
	v_add_f32_dpp v26, v26, v26 quad_perm:[2,3,0,1] row_mask:0xf bank_mask:0xf bound_ctrl:1
	s_waitcnt lgkmcnt(0)
	v_mov_b32_e32 v27, v26
	s_nop 1
	v_permlane16_swap_b32_e32 v26, v27
	v_add_f32_e32 v26, v26, v27
	v_mov_b32_e32 v27, v26
	s_nop 1
	v_permlane32_swap_b32_e32 v26, v27
	v_add_f32_e32 v26, v26, v27
	v_fmamk_f32 v26, v26, 0x3b000000, v206
	v_cmp_gt_f32_e32 vcc, s75, v26
	v_mul_f32_e32 v27, 0x4b800000, v26
	s_nop 0
	v_cndmask_b32_e32 v26, v26, v27, vcc
	v_rsq_f32_e32 v26, v26
	s_nop 0
	v_mul_f32_e32 v27, 0x45800000, v26
	v_cndmask_b32_e32 v26, v26, v27, vcc
	v_pk_mul_f32 v[8:9], v[8:9], v[26:27] op_sel_hi:[1,0]
	v_pk_fma_f32 v[8:9], v[184:185], v[8:9], v[192:193]
	s_nop 0
	v_mul_f32_e32 v27, 0xbfb8aa3b, v8
	v_exp_f32_e32 v27, v27
	s_nop 0
	v_add_f32_e32 v27, 1.0, v27
	v_rcp_f32_e32 v30, v27
	v_mul_f32_e32 v27, 0xbfb8aa3b, v9
	v_exp_f32_e32 v27, v27
	s_nop 0
	v_add_f32_e32 v27, 1.0, v27
	v_pk_mul_f32 v[10:11], v[10:11], v[26:27] op_sel_hi:[1,0]
	v_rcp_f32_e32 v31, v27
	v_pk_fma_f32 v[10:11], v[186:187], v[10:11], v[194:195]
	v_pk_mul_f32 v[8:9], v[8:9], v[30:31]
	v_mul_f32_e32 v27, 0xbfb8aa3b, v10
	v_exp_f32_e32 v27, v27
	s_nop 0
	v_add_f32_e32 v27, 1.0, v27
	v_rcp_f32_e32 v30, v27
	v_mul_f32_e32 v27, 0xbfb8aa3b, v11
	v_exp_f32_e32 v27, v27
	s_nop 0
	v_add_f32_e32 v27, 1.0, v27
	v_pk_mul_f32 v[24:25], v[24:25], v[26:27] op_sel_hi:[1,0]
	v_rcp_f32_e32 v31, v27
	v_pk_fma_f32 v[0:1], v[180:181], v[24:25], v[188:189]
	v_pk_mul_f32 v[10:11], v[10:11], v[30:31]
	v_mul_f32_e32 v4, 0xbfb8aa3b, v0
	v_mul_f32_e32 v5, 0xbfb8aa3b, v1
	v_exp_f32_e32 v4, v4
	v_exp_f32_e32 v5, v5
	v_add_f32_e32 v4, 1.0, v4
	v_add_f32_e32 v5, 1.0, v5
	v_rcp_f32_e32 v4, v4
	v_rcp_f32_e32 v5, v5
	s_nop 0
	v_pk_mul_f32 v[4:5], v[0:1], v[4:5]
	v_pk_mul_f32 v[0:1], v[22:23], v[26:27] op_sel_hi:[1,0]
	s_nop 0
	v_pk_fma_f32 v[0:1], v[0:1], v[182:183], v[190:191]
	s_nop 0
	v_mul_f32_e32 v2, 0xbfb8aa3b, v0
	v_mul_f32_e32 v3, 0xbfb8aa3b, v1
	v_exp_f32_e32 v2, v2
	v_exp_f32_e32 v3, v3
	v_add_f32_e32 v2, 1.0, v2
	v_add_f32_e32 v3, 1.0, v3
	v_rcp_f32_e32 v2, v2
	v_rcp_f32_e32 v3, v3
	s_nop 0
	v_pk_mul_f32 v[6:7], v[0:1], v[2:3]
	v_cvt_pk_bf16_f32 v0, v8, v9
	v_cvt_pk_bf16_f32 v2, v4, v5
	v_lshl_add_u64 v[4:5], s[6:7], 0, v[48:49]
	v_cvt_pk_bf16_f32 v1, v10, v11
	v_cvt_pk_bf16_f32 v3, v6, v7
	v_lshl_add_u64 v[4:5], v[4:5], 0, s[8:9]
	global_store_dwordx4 v[4:5], v[0:3], off
	s_nop 1
	v_add_u32_e32 v0, s69, v76
	ds_read_b128 v[8:11], v0
	ds_read_b128 v[0:3], v0 offset:16
	s_add_u32 s6, s24, s68
	s_addc_u32 s7, s45, s86
	s_lshl_b64 s[6:7], s[6:7], 11
	s_waitcnt lgkmcnt(1)
	v_add_f32_e32 v4, 0, v8
	v_add_f32_e32 v4, v9, v4
	v_add_f32_e32 v4, v10, v4
	v_add_f32_e32 v4, v11, v4
	s_waitcnt lgkmcnt(0)
	v_add_f32_e32 v4, v0, v4
	v_add_f32_e32 v4, v1, v4
	v_add_f32_e32 v4, v2, v4
	v_add_f32_e32 v4, v3, v4
	s_add_u32 s6, s2, s6
	s_addc_u32 s7, s3, s7
	v_add_f32_dpp v4, v4, v4 row_mirror row_mask:0xf bank_mask:0xf bound_ctrl:1
	s_nop 1
	v_add_f32_dpp v4, v4, v4 row_half_mirror row_mask:0xf bank_mask:0xf bound_ctrl:1
	s_nop 1
	v_add_f32_dpp v4, v4, v4 quad_perm:[1,0,3,2] row_mask:0xf bank_mask:0xf bound_ctrl:1
	s_nop 1
	v_add_f32_dpp v4, v4, v4 quad_perm:[2,3,0,1] row_mask:0xf bank_mask:0xf bound_ctrl:1
	s_waitcnt lgkmcnt(0)
	v_mov_b32_e32 v5, v4
	s_nop 1
	v_permlane16_swap_b32_e32 v4, v5
	v_add_f32_e32 v4, v4, v5
	v_mov_b32_e32 v5, v4
	s_nop 1
	v_permlane32_swap_b32_e32 v4, v5
	v_add_f32_e32 v4, v4, v5
	v_mul_f32_e32 v26, 0x3b000000, v4
	v_pk_add_f32 v[22:23], v[2:3], v[26:27] op_sel_hi:[1,0] neg_lo:[0,1] neg_hi:[0,1]
	v_pk_add_f32 v[24:25], v[0:1], v[26:27] op_sel_hi:[1,0] neg_lo:[0,1] neg_hi:[0,1]
	v_pk_add_f32 v[8:9], v[8:9], v[26:27] op_sel_hi:[1,0] neg_lo:[0,1] neg_hi:[0,1]
	v_pk_add_f32 v[10:11], v[10:11], v[26:27] op_sel_hi:[1,0] neg_lo:[0,1] neg_hi:[0,1]
	v_pk_mul_f32 v[26:27], v[8:9], v[8:9]
	v_pk_mul_f32 v[42:43], v[10:11], v[10:11]
	v_add_f32_e32 v26, v26, v27
	v_add_f32_e32 v26, v42, v26
	v_pk_mul_f32 v[40:41], v[24:25], v[24:25]
	v_add_f32_e32 v26, v43, v26
	v_add_f32_e32 v26, v40, v26
	v_pk_mul_f32 v[38:39], v[22:23], v[22:23]
	v_add_f32_e32 v26, v41, v26
	v_add_f32_e32 v26, v38, v26
	v_add_f32_e32 v26, v39, v26
	s_nop 1
	v_add_f32_dpp v26, v26, v26 row_mirror row_mask:0xf bank_mask:0xf bound_ctrl:1
	s_nop 1
	v_add_f32_dpp v26, v26, v26 row_half_mirror row_mask:0xf bank_mask:0xf bound_ctrl:1
	s_nop 1
	v_add_f32_dpp v26, v26, v26 quad_perm:[1,0,3,2] row_mask:0xf bank_mask:0xf bound_ctrl:1
	s_nop 1
	v_add_f32_dpp v26, v26, v26 quad_perm:[2,3,0,1] row_mask:0xf bank_mask:0xf bound_ctrl:1
	s_waitcnt lgkmcnt(0)
	v_mov_b32_e32 v27, v26
	s_nop 1
	v_permlane16_swap_b32_e32 v26, v27
	v_add_f32_e32 v26, v26, v27
	v_mov_b32_e32 v27, v26
	s_nop 1
	v_permlane32_swap_b32_e32 v26, v27
	v_add_f32_e32 v26, v26, v27
	v_fmamk_f32 v26, v26, 0x3b000000, v206
	v_cmp_gt_f32_e32 vcc, s75, v26
	v_mul_f32_e32 v27, 0x4b800000, v26
	s_nop 0
	v_cndmask_b32_e32 v26, v26, v27, vcc
	v_rsq_f32_e32 v26, v26
	s_nop 0
	v_mul_f32_e32 v27, 0x45800000, v26
	v_cndmask_b32_e32 v26, v26, v27, vcc
	v_pk_mul_f32 v[8:9], v[8:9], v[26:27] op_sel_hi:[1,0]
	v_pk_fma_f32 v[8:9], v[184:185], v[8:9], v[192:193]
	s_nop 0
	v_mul_f32_e32 v27, 0xbfb8aa3b, v8
	v_exp_f32_e32 v27, v27
	s_nop 0
	v_add_f32_e32 v27, 1.0, v27
	v_rcp_f32_e32 v30, v27
	v_mul_f32_e32 v27, 0xbfb8aa3b, v9
	v_exp_f32_e32 v27, v27
	s_nop 0
	v_add_f32_e32 v27, 1.0, v27
	v_pk_mul_f32 v[10:11], v[10:11], v[26:27] op_sel_hi:[1,0]
	v_rcp_f32_e32 v31, v27
	v_pk_fma_f32 v[10:11], v[186:187], v[10:11], v[194:195]
	v_pk_mul_f32 v[8:9], v[8:9], v[30:31]
	v_mul_f32_e32 v27, 0xbfb8aa3b, v10
	v_exp_f32_e32 v27, v27
	s_nop 0
	v_add_f32_e32 v27, 1.0, v27
	v_rcp_f32_e32 v30, v27
	v_mul_f32_e32 v27, 0xbfb8aa3b, v11
	v_exp_f32_e32 v27, v27
	s_nop 0
	v_add_f32_e32 v27, 1.0, v27
	v_pk_mul_f32 v[24:25], v[24:25], v[26:27] op_sel_hi:[1,0]
	v_rcp_f32_e32 v31, v27
	v_pk_fma_f32 v[0:1], v[180:181], v[24:25], v[188:189]
	v_pk_mul_f32 v[10:11], v[10:11], v[30:31]
	v_mul_f32_e32 v4, 0xbfb8aa3b, v0
	v_mul_f32_e32 v5, 0xbfb8aa3b, v1
	v_exp_f32_e32 v4, v4
	v_exp_f32_e32 v5, v5
	v_add_f32_e32 v4, 1.0, v4
	v_add_f32_e32 v5, 1.0, v5
	v_rcp_f32_e32 v4, v4
	v_rcp_f32_e32 v5, v5
	s_nop 0
	v_pk_mul_f32 v[4:5], v[0:1], v[4:5]
	v_pk_mul_f32 v[0:1], v[22:23], v[26:27] op_sel_hi:[1,0]
	s_nop 0
	v_pk_fma_f32 v[0:1], v[0:1], v[182:183], v[190:191]
	s_nop 0
	v_mul_f32_e32 v2, 0xbfb8aa3b, v0
	v_mul_f32_e32 v3, 0xbfb8aa3b, v1
	v_exp_f32_e32 v2, v2
	v_exp_f32_e32 v3, v3
	v_add_f32_e32 v2, 1.0, v2
	v_add_f32_e32 v3, 1.0, v3
	v_rcp_f32_e32 v2, v2
	v_rcp_f32_e32 v3, v3
	s_nop 0
	v_pk_mul_f32 v[6:7], v[0:1], v[2:3]
	v_cvt_pk_bf16_f32 v0, v8, v9
	v_cvt_pk_bf16_f32 v2, v4, v5
	v_lshl_add_u64 v[4:5], s[6:7], 0, v[48:49]
	v_cvt_pk_bf16_f32 v1, v10, v11
	v_cvt_pk_bf16_f32 v3, v6, v7
	v_lshl_add_u64 v[4:5], v[4:5], 0, s[8:9]
	global_store_dwordx4 v[4:5], v[0:3], off
	s_nop 1
	v_add_u32_e32 v0, s88, v76
	ds_read_b128 v[8:11], v0
	ds_read_b128 v[0:3], v0 offset:16
	s_add_u32 s6, s24, s87
	s_addc_u32 s7, s45, s89
	s_lshl_b64 s[6:7], s[6:7], 11
	s_waitcnt lgkmcnt(1)
	v_add_f32_e32 v4, 0, v8
	v_add_f32_e32 v4, v9, v4
	v_add_f32_e32 v4, v10, v4
	v_add_f32_e32 v4, v11, v4
	s_waitcnt lgkmcnt(0)
	v_add_f32_e32 v4, v0, v4
	v_add_f32_e32 v4, v1, v4
	v_add_f32_e32 v4, v2, v4
	v_add_f32_e32 v4, v3, v4
	s_add_u32 s6, s2, s6
	s_addc_u32 s7, s3, s7
	v_add_f32_dpp v4, v4, v4 row_mirror row_mask:0xf bank_mask:0xf bound_ctrl:1
	s_add_i32 s60, s60, s73
	s_nop 0
	v_add_f32_dpp v4, v4, v4 row_half_mirror row_mask:0xf bank_mask:0xf bound_ctrl:1
	s_nop 1
	v_add_f32_dpp v4, v4, v4 quad_perm:[1,0,3,2] row_mask:0xf bank_mask:0xf bound_ctrl:1
	s_nop 1
	v_add_f32_dpp v4, v4, v4 quad_perm:[2,3,0,1] row_mask:0xf bank_mask:0xf bound_ctrl:1
	s_waitcnt lgkmcnt(0)
	v_mov_b32_e32 v5, v4
	s_nop 1
	v_permlane16_swap_b32_e32 v4, v5
	v_add_f32_e32 v4, v4, v5
	v_mov_b32_e32 v5, v4
	s_nop 1
	v_permlane32_swap_b32_e32 v4, v5
	v_add_f32_e32 v4, v4, v5
	v_mul_f32_e32 v26, 0x3b000000, v4
	v_pk_add_f32 v[22:23], v[2:3], v[26:27] op_sel_hi:[1,0] neg_lo:[0,1] neg_hi:[0,1]
	v_pk_add_f32 v[24:25], v[0:1], v[26:27] op_sel_hi:[1,0] neg_lo:[0,1] neg_hi:[0,1]
	v_pk_add_f32 v[8:9], v[8:9], v[26:27] op_sel_hi:[1,0] neg_lo:[0,1] neg_hi:[0,1]
	v_pk_add_f32 v[10:11], v[10:11], v[26:27] op_sel_hi:[1,0] neg_lo:[0,1] neg_hi:[0,1]
	v_pk_mul_f32 v[26:27], v[8:9], v[8:9]
	v_pk_mul_f32 v[42:43], v[10:11], v[10:11]
	v_add_f32_e32 v26, v26, v27
	v_add_f32_e32 v26, v42, v26
	v_pk_mul_f32 v[40:41], v[24:25], v[24:25]
	v_add_f32_e32 v26, v43, v26
	v_add_f32_e32 v26, v40, v26
	v_pk_mul_f32 v[38:39], v[22:23], v[22:23]
	v_add_f32_e32 v26, v41, v26
	v_add_f32_e32 v26, v38, v26
	v_add_f32_e32 v26, v39, v26
	s_nop 1
	v_add_f32_dpp v26, v26, v26 row_mirror row_mask:0xf bank_mask:0xf bound_ctrl:1
	s_nop 1
	v_add_f32_dpp v26, v26, v26 row_half_mirror row_mask:0xf bank_mask:0xf bound_ctrl:1
	s_nop 1
	v_add_f32_dpp v26, v26, v26 quad_perm:[1,0,3,2] row_mask:0xf bank_mask:0xf bound_ctrl:1
	s_nop 1
	v_add_f32_dpp v26, v26, v26 quad_perm:[2,3,0,1] row_mask:0xf bank_mask:0xf bound_ctrl:1
	s_waitcnt lgkmcnt(0)
	v_mov_b32_e32 v27, v26
	s_nop 1
	v_permlane16_swap_b32_e32 v26, v27
	v_add_f32_e32 v26, v26, v27
	v_mov_b32_e32 v27, v26
	s_nop 1
	v_permlane32_swap_b32_e32 v26, v27
	v_add_f32_e32 v26, v26, v27
	v_fmamk_f32 v26, v26, 0x3b000000, v206
	v_cmp_gt_f32_e32 vcc, s75, v26
	v_mul_f32_e32 v27, 0x4b800000, v26
	s_nop 0
	v_cndmask_b32_e32 v26, v26, v27, vcc
	v_rsq_f32_e32 v26, v26
	s_nop 0
	v_mul_f32_e32 v27, 0x45800000, v26
	v_cndmask_b32_e32 v26, v26, v27, vcc
	v_pk_mul_f32 v[8:9], v[8:9], v[26:27] op_sel_hi:[1,0]
	v_pk_fma_f32 v[8:9], v[184:185], v[8:9], v[192:193]
	s_nop 0
	v_mul_f32_e32 v27, 0xbfb8aa3b, v8
	v_exp_f32_e32 v27, v27
	s_nop 0
	v_add_f32_e32 v27, 1.0, v27
	v_rcp_f32_e32 v28, v27
	v_mul_f32_e32 v27, 0xbfb8aa3b, v9
	v_exp_f32_e32 v27, v27
	s_nop 0
	v_add_f32_e32 v27, 1.0, v27
	v_pk_mul_f32 v[10:11], v[10:11], v[26:27] op_sel_hi:[1,0]
	v_rcp_f32_e32 v29, v27
	v_pk_fma_f32 v[10:11], v[186:187], v[10:11], v[194:195]
	v_pk_mul_f32 v[8:9], v[8:9], v[28:29]
	v_mul_f32_e32 v27, 0xbfb8aa3b, v10
	v_exp_f32_e32 v27, v27
	s_nop 0
	v_add_f32_e32 v27, 1.0, v27
	v_rcp_f32_e32 v28, v27
	v_mul_f32_e32 v27, 0xbfb8aa3b, v11
	v_exp_f32_e32 v27, v27
	s_nop 0
	v_add_f32_e32 v27, 1.0, v27
	v_pk_mul_f32 v[24:25], v[24:25], v[26:27] op_sel_hi:[1,0]
	v_rcp_f32_e32 v29, v27
	v_pk_fma_f32 v[0:1], v[180:181], v[24:25], v[188:189]
	v_pk_mul_f32 v[10:11], v[10:11], v[28:29]
	v_mul_f32_e32 v4, 0xbfb8aa3b, v0
	v_mul_f32_e32 v5, 0xbfb8aa3b, v1
	v_exp_f32_e32 v4, v4
	v_exp_f32_e32 v5, v5
	v_add_f32_e32 v4, 1.0, v4
	v_add_f32_e32 v5, 1.0, v5
	v_rcp_f32_e32 v4, v4
	v_rcp_f32_e32 v5, v5
	s_nop 0
	v_pk_mul_f32 v[4:5], v[0:1], v[4:5]
	v_pk_mul_f32 v[0:1], v[22:23], v[26:27] op_sel_hi:[1,0]
	s_nop 0
	v_pk_fma_f32 v[0:1], v[0:1], v[182:183], v[190:191]
	s_nop 0
	v_mul_f32_e32 v2, 0xbfb8aa3b, v0
	v_mul_f32_e32 v3, 0xbfb8aa3b, v1
	v_exp_f32_e32 v2, v2
	v_exp_f32_e32 v3, v3
	v_add_f32_e32 v2, 1.0, v2
	v_add_f32_e32 v3, 1.0, v3
	v_rcp_f32_e32 v2, v2
	v_rcp_f32_e32 v3, v3
	s_nop 0
	v_pk_mul_f32 v[6:7], v[0:1], v[2:3]
	v_cvt_pk_bf16_f32 v2, v4, v5
	v_lshl_add_u64 v[4:5], s[6:7], 0, v[48:49]
	v_cvt_pk_bf16_f32 v0, v8, v9
	v_cvt_pk_bf16_f32 v1, v10, v11
	v_cvt_pk_bf16_f32 v3, v6, v7
	v_lshl_add_u64 v[4:5], v[4:5], 0, s[8:9]
	global_store_dwordx4 v[4:5], v[0:3], off
	s_nop 1
	v_readlane_b32 s6, v255, 5
	s_add_i32 s90, s90, s6
	s_cmp_gt_i32 s60, 63
	s_barrier
	s_cbranch_scc1 .LBB0_897
